# attention / retention / gMLP epilogues: packed bf16 pairs staged through LDS and stored as full-row dwordx4 segments (8 stores per wave instead of 64 dword stores)
# speedup vs baseline: 1.0004x; 1.0004x over previous
; #define LAS __attribute__((address_space(3)))
; __device__ __forceinline__ float bf2f(unsigned h) { return __uint_as_float(h << 16); }
; __device__ __forceinline__ unsigned cvt_pk_bf16(float lo, float hi) { unsigned r; asm volatile("v_cvt_pk_bf16_f32 %0, %1, %2" : "=v"(r) : "v"(lo), "v"(hi)); return r; }
; __device__ __forceinline__ int crow(int r, int hi) { return (r & 3) + 8 * (r >> 2) + 4 * hi; }
; __device__ __forceinline__ void gmlp_phase(const bf16_t* GU, const bf16_t* GV, const float* lng, const float* lnb, const float* wsp, const float* bsp, bf16_t* Y, lptr lds, int blk, int G, int tid_) {
;     ...
;         const LAS bf16_t* up = (const LAS bf16_t*)(lds + 65536 + ui * 32768 + (32 * tb) * 256) + r32; bf16_t* yp = Y + ((size_t)(b * SEQ + n * 128 + 32 * tb)) * DM + 1536 + g * HD + r32;
; #pragma unroll
;         for (int r = 0; r < 16; ++r) { const int tr = crow(r, hi); const float bt = btv[r];
;             float v0 = bf2f(up[tr * HD]) * (acc[0][r] + bt), v1 = bf2f(up[tr * HD + 32]) * (acc[1][r] + bt), v2 = bf2f(up[tr * HD + 64]) * (acc[2][r] + bt), v3 = bf2f(up[tr * HD + 96]) * (acc[3][r] + bt);
;             float ss = (v0 * v0 + v1 * v1) + (v2 * v2 + v3 * v3);
;             ss += __shfl_xor(ss, 1); ss += __shfl_xor(ss, 2); ss += __shfl_xor(ss, 4); ss += __shfl_xor(ss, 8); ss += __shfl_xor(ss, 16);
;             const float rs = rsqrtf(ss * (1.0f / 128.0f) + EPS);
;             v0 *= rs; v1 *= rs; v2 *= rs; v3 *= rs;
;             const float n0 = __shfl_xor(v0, 1), n1 = __shfl_xor(v1, 1), n2 = __shfl_xor(v2, 1), n3 = __shfl_xor(v3, 1);
;             if ((r32 & 1) == 0) { bf16_t* op = yp + (size_t)tr * DM;
;                 *(unsigned*)(op) = cvt_pk_bf16(v0, n0); *(unsigned*)(op + 32) = cvt_pk_bf16(v1, n1); *(unsigned*)(op + 64) = cvt_pk_bf16(v2, n2); *(unsigned*)(op + 96) = cvt_pk_bf16(v3, n3); } }
.LBB0_628:
	s_lshl_b32 s4, s29, 13
	s_add_i32 s30, s30, s4
	s_lshl_b32 s4, s28, 12
	s_or_b32 s4, s4, s27
	s_or_b32 s4, s4, s34
	s_ashr_i32 s5, s4, 31
	s_lshl_b64 s[4:5], s[4:5], 12
	s_add_u32 s4, s22, s4
	s_addc_u32 s5, s23, s5
	s_lshl_b32 s6, s26, 1
	s_add_u32 s4, s4, s6
	s_addc_u32 s5, s5, 0
	s_add_u32 s4, s4, 0x39800c00
	s_addc_u32 s5, s5, 0
	v_lshlrev_b32_e32 v162, 1, v130
	v_and_b32_e32 v136, 1, v136
	v_add_u32_e32 v138, s30, v162
	v_cmp_eq_u32_e32 vcc, 0, v136
	v_lshl_add_u32 v138, v139, 10, v138
	ds_read_u16 v140, v138
	ds_read_u16 v141, v138 offset:64
	ds_read_u16 v142, v138 offset:128
	ds_read_u16 v143, v138 offset:192
	ds_read_u16 v144, v138 offset:256
	ds_read_u16 v145, v138 offset:320
	ds_read_u16 v146, v138 offset:384
	ds_read_u16 v147, v138 offset:448
	ds_read_u16 v156, v138 offset:512
	ds_read_u16 v157, v138 offset:576
	ds_read_u16 v158, v138 offset:640
	ds_read_u16 v159, v138 offset:704
	ds_read_u16 v160, v138 offset:768
	ds_read_u16 v161, v138 offset:832
	ds_read_u16 v130, v138 offset:896
	ds_read_u16 v131, v138 offset:960
	v_pk_add_f32 v[18:19], v[18:19], v[126:127]
	v_pk_add_f32 v[2:3], v[2:3], v[126:127]
	v_pk_add_f32 v[50:51], v[50:51], v[126:127]
	v_pk_add_f32 v[34:35], v[34:35], v[126:127]
	v_pk_add_f32 v[20:21], v[20:21], v[128:129]
	v_pk_add_f32 v[4:5], v[4:5], v[128:129]
	v_pk_add_f32 v[52:53], v[52:53], v[128:129]
	v_pk_add_f32 v[36:37], v[36:37], v[128:129]
	s_waitcnt lgkmcnt(0)
	v_lshlrev_b32_e32 v140, 16, v140
	v_lshlrev_b32_e32 v141, 16, v141
	v_lshlrev_b32_e32 v142, 16, v142
	v_lshlrev_b32_e32 v143, 16, v143
	v_lshlrev_b32_e32 v144, 16, v144
	v_lshlrev_b32_e32 v145, 16, v145
	v_lshlrev_b32_e32 v146, 16, v146
	v_lshlrev_b32_e32 v147, 16, v147
	v_lshlrev_b32_e32 v156, 16, v156
	v_lshlrev_b32_e32 v157, 16, v157
	v_lshlrev_b32_e32 v158, 16, v158
	v_lshlrev_b32_e32 v159, 16, v159
	v_lshlrev_b32_e32 v160, 16, v160
	v_lshlrev_b32_e32 v161, 16, v161
	v_lshlrev_b32_e32 v130, 16, v130
	v_lshlrev_b32_e32 v131, 16, v131
	v_mul_f32_e32 v18, v18, v140
	v_mul_f32_e32 v2, v2, v141
	v_mul_f32_e32 v50, v50, v142
	v_mul_f32_e32 v34, v34, v143
	v_mul_f32_e32 v19, v19, v144
	v_mul_f32_e32 v3, v3, v145
	v_mul_f32_e32 v51, v51, v146
	v_mul_f32_e32 v35, v35, v147
	v_mul_f32_e32 v20, v20, v156
	v_mul_f32_e32 v4, v4, v157
	v_mul_f32_e32 v52, v52, v158
	v_mul_f32_e32 v36, v36, v159
	v_mul_f32_e32 v21, v21, v160
	v_mul_f32_e32 v5, v5, v161
	v_mul_f32_e32 v53, v53, v130
	v_mul_f32_e32 v37, v37, v131
	v_pk_mul_f32 v[148:149], v[18:19], v[18:19]
	v_pk_mul_f32 v[150:151], v[20:21], v[20:21]
	v_pk_fma_f32 v[148:149], v[2:3], v[2:3], v[148:149]
	v_pk_fma_f32 v[150:151], v[4:5], v[4:5], v[150:151]
	v_pk_fma_f32 v[148:149], v[50:51], v[50:51], v[148:149]
	v_pk_fma_f32 v[150:151], v[52:53], v[52:53], v[150:151]
	v_pk_fma_f32 v[148:149], v[34:35], v[34:35], v[148:149]
	v_pk_fma_f32 v[150:151], v[36:37], v[36:37], v[150:151]
	s_nop 1
	v_add_f32_dpp v148, v148, v148 quad_perm:[1,0,3,2] row_mask:0xf bank_mask:0xf
	v_add_f32_dpp v149, v149, v149 quad_perm:[1,0,3,2] row_mask:0xf bank_mask:0xf
	v_add_f32_dpp v150, v150, v150 quad_perm:[1,0,3,2] row_mask:0xf bank_mask:0xf
	v_add_f32_dpp v151, v151, v151 quad_perm:[1,0,3,2] row_mask:0xf bank_mask:0xf
	v_add_f32_dpp v148, v148, v148 quad_perm:[2,3,0,1] row_mask:0xf bank_mask:0xf
	v_add_f32_dpp v149, v149, v149 quad_perm:[2,3,0,1] row_mask:0xf bank_mask:0xf
	v_add_f32_dpp v150, v150, v150 quad_perm:[2,3,0,1] row_mask:0xf bank_mask:0xf
	v_add_f32_dpp v151, v151, v151 quad_perm:[2,3,0,1] row_mask:0xf bank_mask:0xf
	v_add_f32_dpp v148, v148, v148 row_half_mirror row_mask:0xf bank_mask:0xf
	v_add_f32_dpp v149, v149, v149 row_half_mirror row_mask:0xf bank_mask:0xf
	v_add_f32_dpp v150, v150, v150 row_half_mirror row_mask:0xf bank_mask:0xf
	v_add_f32_dpp v151, v151, v151 row_half_mirror row_mask:0xf bank_mask:0xf
	v_add_f32_dpp v148, v148, v148 row_mirror row_mask:0xf bank_mask:0xf
	v_add_f32_dpp v149, v149, v149 row_mirror row_mask:0xf bank_mask:0xf
	v_add_f32_dpp v150, v150, v150 row_mirror row_mask:0xf bank_mask:0xf
	v_add_f32_dpp v151, v151, v151 row_mirror row_mask:0xf bank_mask:0xf
	v_mov_b32_e32 v152, v148
	v_mov_b32_e32 v153, v149
	v_mov_b32_e32 v154, v150
	v_mov_b32_e32 v155, v151
	v_permlane16_swap_b32_e32 v148, v152
	v_permlane16_swap_b32_e32 v149, v153
	v_permlane16_swap_b32_e32 v150, v154
	v_permlane16_swap_b32_e32 v151, v155
	v_add_f32_e32 v148, v148, v152
	v_add_f32_e32 v149, v149, v153
	v_add_f32_e32 v150, v150, v154
	v_add_f32_e32 v151, v151, v155
	v_fmamk_f32 v148, v148, 0x3c000000, v192
	v_fmamk_f32 v149, v149, 0x3c000000, v192
	v_fmamk_f32 v150, v150, 0x3c000000, v192
	v_fmamk_f32 v151, v151, 0x3c000000, v192
	v_rsq_f32_e32 v148, v148
	v_rsq_f32_e32 v149, v149
	v_rsq_f32_e32 v150, v150
	v_rsq_f32_e32 v151, v151
	s_nop 0
	v_pk_mul_f32 v[18:19], v[18:19], v[148:149]
	v_pk_mul_f32 v[2:3], v[2:3], v[148:149]
	v_pk_mul_f32 v[50:51], v[50:51], v[148:149]
	v_pk_mul_f32 v[34:35], v[34:35], v[148:149]
	v_pk_mul_f32 v[20:21], v[20:21], v[150:151]
	v_pk_mul_f32 v[4:5], v[4:5], v[150:151]
	v_pk_mul_f32 v[52:53], v[52:53], v[150:151]
	v_pk_mul_f32 v[36:37], v[36:37], v[150:151]
	s_nop 0
	v_mov_b32_dpp v152, v18 quad_perm:[1,0,3,2] row_mask:0xf bank_mask:0xf
	v_mov_b32_dpp v153, v2 quad_perm:[1,0,3,2] row_mask:0xf bank_mask:0xf
	v_mov_b32_dpp v154, v50 quad_perm:[1,0,3,2] row_mask:0xf bank_mask:0xf
	v_mov_b32_dpp v155, v34 quad_perm:[1,0,3,2] row_mask:0xf bank_mask:0xf
	v_cvt_pk_bf16_f32 v18, v18, v152
	v_cvt_pk_bf16_f32 v2, v2, v153
	v_cvt_pk_bf16_f32 v50, v50, v154
	v_cvt_pk_bf16_f32 v34, v34, v155
	v_mov_b32_dpp v152, v19 quad_perm:[1,0,3,2] row_mask:0xf bank_mask:0xf
; __device__ __forceinline__ float bf2f(unsigned h) { return __uint_as_float(h << 16); }
; __device__ __forceinline__ int crow(int r, int hi) { return (r & 3) + 8 * (r >> 2) + 4 * hi; }
; __device__ __forceinline__ void gmlp_phase(const bf16_t* GU, const bf16_t* GV, const float* lng, const float* lnb, const float* wsp, const float* bsp, bf16_t* Y, lptr lds, int blk, int G, int tid_) {
;     ...
;         for (int r = 0; r < 16; ++r) { const int tr = crow(r, hi); const float bt = btv[r];
;             float v0 = bf2f(up[tr * HD]) * (acc[0][r] + bt), v1 = bf2f(up[tr * HD + 32]) * (acc[1][r] + bt), v2 = bf2f(up[tr * HD + 64]) * (acc[2][r] + bt), v3 = bf2f(up[tr * HD + 96]) * (acc[3][r] + bt);
;             float ss = (v0 * v0 + v1 * v1) + (v2 * v2 + v3 * v3);
;             ss += __shfl_xor(ss, 1); ss += __shfl_xor(ss, 2); ss += __shfl_xor(ss, 4); ss += __shfl_xor(ss, 8); ss += __shfl_xor(ss, 16);
;             const float rs = rsqrtf(ss * (1.0f / 128.0f) + EPS);
;             v0 *= rs; v1 *= rs; v2 *= rs; v3 *= rs;
;             const float n0 = __shfl_xor(v0, 1), n1 = __shfl_xor(v1, 1), n2 = __shfl_xor(v2, 1), n3 = __shfl_xor(v3, 1);
	v_mov_b32_dpp v153, v3 quad_perm:[1,0,3,2] row_mask:0xf bank_mask:0xf
	v_mov_b32_dpp v154, v51 quad_perm:[1,0,3,2] row_mask:0xf bank_mask:0xf
	v_mov_b32_dpp v155, v35 quad_perm:[1,0,3,2] row_mask:0xf bank_mask:0xf
	v_cvt_pk_bf16_f32 v19, v19, v152
	v_cvt_pk_bf16_f32 v3, v3, v153
	v_cvt_pk_bf16_f32 v51, v51, v154
	v_cvt_pk_bf16_f32 v35, v35, v155
	v_mov_b32_dpp v152, v20 quad_perm:[1,0,3,2] row_mask:0xf bank_mask:0xf
	v_mov_b32_dpp v153, v4 quad_perm:[1,0,3,2] row_mask:0xf bank_mask:0xf
	v_mov_b32_dpp v154, v52 quad_perm:[1,0,3,2] row_mask:0xf bank_mask:0xf
	v_mov_b32_dpp v155, v36 quad_perm:[1,0,3,2] row_mask:0xf bank_mask:0xf
	v_cvt_pk_bf16_f32 v20, v20, v152
	v_cvt_pk_bf16_f32 v4, v4, v153
	v_cvt_pk_bf16_f32 v52, v52, v154
	v_cvt_pk_bf16_f32 v36, v36, v155
	v_mov_b32_dpp v152, v21 quad_perm:[1,0,3,2] row_mask:0xf bank_mask:0xf
	v_mov_b32_dpp v153, v5 quad_perm:[1,0,3,2] row_mask:0xf bank_mask:0xf
	v_mov_b32_dpp v154, v53 quad_perm:[1,0,3,2] row_mask:0xf bank_mask:0xf
	v_mov_b32_dpp v155, v37 quad_perm:[1,0,3,2] row_mask:0xf bank_mask:0xf
	v_cvt_pk_bf16_f32 v21, v21, v152
	v_cvt_pk_bf16_f32 v5, v5, v153
	v_cvt_pk_bf16_f32 v53, v53, v154
	v_cvt_pk_bf16_f32 v37, v37, v155
	ds_read_u16 v140, v138 offset:2048
	ds_read_u16 v141, v138 offset:2112
	ds_read_u16 v142, v138 offset:2176
	ds_read_u16 v143, v138 offset:2240
	ds_read_u16 v144, v138 offset:2304
	ds_read_u16 v145, v138 offset:2368
	ds_read_u16 v146, v138 offset:2432
	ds_read_u16 v147, v138 offset:2496
	ds_read_u16 v156, v138 offset:2560
	ds_read_u16 v157, v138 offset:2624
	ds_read_u16 v158, v138 offset:2688
	ds_read_u16 v159, v138 offset:2752
	ds_read_u16 v160, v138 offset:2816
	ds_read_u16 v161, v138 offset:2880
	ds_read_u16 v130, v138 offset:2944
	ds_read_u16 v131, v138 offset:3008
	v_pk_add_f32 v[22:23], v[22:23], v[122:123]
	v_pk_add_f32 v[6:7], v[6:7], v[122:123]
	v_pk_add_f32 v[54:55], v[54:55], v[122:123]
	v_pk_add_f32 v[38:39], v[38:39], v[122:123]
	v_pk_add_f32 v[24:25], v[24:25], v[124:125]
	v_pk_add_f32 v[8:9], v[8:9], v[124:125]
	v_pk_add_f32 v[56:57], v[56:57], v[124:125]
	v_pk_add_f32 v[40:41], v[40:41], v[124:125]
	s_waitcnt lgkmcnt(0)
	v_lshlrev_b32_e32 v140, 16, v140
	v_lshlrev_b32_e32 v141, 16, v141
	v_lshlrev_b32_e32 v142, 16, v142
	v_lshlrev_b32_e32 v143, 16, v143
	v_lshlrev_b32_e32 v144, 16, v144
	v_lshlrev_b32_e32 v145, 16, v145
	v_lshlrev_b32_e32 v146, 16, v146
	v_lshlrev_b32_e32 v147, 16, v147
	v_lshlrev_b32_e32 v156, 16, v156
	v_lshlrev_b32_e32 v157, 16, v157
	v_lshlrev_b32_e32 v158, 16, v158
	v_lshlrev_b32_e32 v159, 16, v159
	v_lshlrev_b32_e32 v160, 16, v160
	v_lshlrev_b32_e32 v161, 16, v161
	v_lshlrev_b32_e32 v130, 16, v130
	v_lshlrev_b32_e32 v131, 16, v131
	v_mul_f32_e32 v22, v22, v140
	v_mul_f32_e32 v6, v6, v141
	v_mul_f32_e32 v54, v54, v142
	v_mul_f32_e32 v38, v38, v143
	v_mul_f32_e32 v23, v23, v144
	v_mul_f32_e32 v7, v7, v145
	v_mul_f32_e32 v55, v55, v146
	v_mul_f32_e32 v39, v39, v147
	v_mul_f32_e32 v24, v24, v156
	v_mul_f32_e32 v8, v8, v157
	v_mul_f32_e32 v56, v56, v158
	v_mul_f32_e32 v40, v40, v159
	v_mul_f32_e32 v25, v25, v160
	v_mul_f32_e32 v9, v9, v161
	v_mul_f32_e32 v57, v57, v130
	v_mul_f32_e32 v41, v41, v131
	v_pk_mul_f32 v[148:149], v[22:23], v[22:23]
	v_pk_mul_f32 v[150:151], v[24:25], v[24:25]
	v_pk_fma_f32 v[148:149], v[6:7], v[6:7], v[148:149]
	v_pk_fma_f32 v[150:151], v[8:9], v[8:9], v[150:151]
	v_pk_fma_f32 v[148:149], v[54:55], v[54:55], v[148:149]
	v_pk_fma_f32 v[150:151], v[56:57], v[56:57], v[150:151]
	v_pk_fma_f32 v[148:149], v[38:39], v[38:39], v[148:149]
	v_pk_fma_f32 v[150:151], v[40:41], v[40:41], v[150:151]
	s_nop 1
	v_add_f32_dpp v148, v148, v148 quad_perm:[1,0,3,2] row_mask:0xf bank_mask:0xf
	v_add_f32_dpp v149, v149, v149 quad_perm:[1,0,3,2] row_mask:0xf bank_mask:0xf
	v_add_f32_dpp v150, v150, v150 quad_perm:[1,0,3,2] row_mask:0xf bank_mask:0xf
	v_add_f32_dpp v151, v151, v151 quad_perm:[1,0,3,2] row_mask:0xf bank_mask:0xf
	v_add_f32_dpp v148, v148, v148 quad_perm:[2,3,0,1] row_mask:0xf bank_mask:0xf
	v_add_f32_dpp v149, v149, v149 quad_perm:[2,3,0,1] row_mask:0xf bank_mask:0xf
	v_add_f32_dpp v150, v150, v150 quad_perm:[2,3,0,1] row_mask:0xf bank_mask:0xf
	v_add_f32_dpp v151, v151, v151 quad_perm:[2,3,0,1] row_mask:0xf bank_mask:0xf
	v_add_f32_dpp v148, v148, v148 row_half_mirror row_mask:0xf bank_mask:0xf
	v_add_f32_dpp v149, v149, v149 row_half_mirror row_mask:0xf bank_mask:0xf
	v_add_f32_dpp v150, v150, v150 row_half_mirror row_mask:0xf bank_mask:0xf
	v_add_f32_dpp v151, v151, v151 row_half_mirror row_mask:0xf bank_mask:0xf
	v_add_f32_dpp v148, v148, v148 row_mirror row_mask:0xf bank_mask:0xf
	v_add_f32_dpp v149, v149, v149 row_mirror row_mask:0xf bank_mask:0xf
	v_add_f32_dpp v150, v150, v150 row_mirror row_mask:0xf bank_mask:0xf
	v_add_f32_dpp v151, v151, v151 row_mirror row_mask:0xf bank_mask:0xf
	v_mov_b32_e32 v152, v148
	v_mov_b32_e32 v153, v149
	v_mov_b32_e32 v154, v150
	v_mov_b32_e32 v155, v151
	v_permlane16_swap_b32_e32 v148, v152
	v_permlane16_swap_b32_e32 v149, v153
	v_permlane16_swap_b32_e32 v150, v154
	v_permlane16_swap_b32_e32 v151, v155
	v_add_f32_e32 v148, v148, v152
	v_add_f32_e32 v149, v149, v153
	v_add_f32_e32 v150, v150, v154
	v_add_f32_e32 v151, v151, v155
	v_fmamk_f32 v148, v148, 0x3c000000, v192
	v_fmamk_f32 v149, v149, 0x3c000000, v192
	v_fmamk_f32 v150, v150, 0x3c000000, v192
	v_fmamk_f32 v151, v151, 0x3c000000, v192
	v_rsq_f32_e32 v148, v148
	v_rsq_f32_e32 v149, v149
	v_rsq_f32_e32 v150, v150
	v_rsq_f32_e32 v151, v151
	s_nop 0
	v_pk_mul_f32 v[22:23], v[22:23], v[148:149]
	v_pk_mul_f32 v[6:7], v[6:7], v[148:149]
	v_pk_mul_f32 v[54:55], v[54:55], v[148:149]
	v_pk_mul_f32 v[38:39], v[38:39], v[148:149]
; __device__ __forceinline__ float bf2f(unsigned h) { return __uint_as_float(h << 16); }
; __device__ __forceinline__ int crow(int r, int hi) { return (r & 3) + 8 * (r >> 2) + 4 * hi; }
; __device__ __forceinline__ void gmlp_phase(const bf16_t* GU, const bf16_t* GV, const float* lng, const float* lnb, const float* wsp, const float* bsp, bf16_t* Y, lptr lds, int blk, int G, int tid_) {
;     ...
;         for (int r = 0; r < 16; ++r) { const int tr = crow(r, hi); const float bt = btv[r];
;             float v0 = bf2f(up[tr * HD]) * (acc[0][r] + bt), v1 = bf2f(up[tr * HD + 32]) * (acc[1][r] + bt), v2 = bf2f(up[tr * HD + 64]) * (acc[2][r] + bt), v3 = bf2f(up[tr * HD + 96]) * (acc[3][r] + bt);
;             float ss = (v0 * v0 + v1 * v1) + (v2 * v2 + v3 * v3);
;             ss += __shfl_xor(ss, 1); ss += __shfl_xor(ss, 2); ss += __shfl_xor(ss, 4); ss += __shfl_xor(ss, 8); ss += __shfl_xor(ss, 16);
;             const float rs = rsqrtf(ss * (1.0f / 128.0f) + EPS);
;             v0 *= rs; v1 *= rs; v2 *= rs; v3 *= rs;
;             const float n0 = __shfl_xor(v0, 1), n1 = __shfl_xor(v1, 1), n2 = __shfl_xor(v2, 1), n3 = __shfl_xor(v3, 1);
	v_pk_mul_f32 v[24:25], v[24:25], v[150:151]
	v_pk_mul_f32 v[8:9], v[8:9], v[150:151]
	v_pk_mul_f32 v[56:57], v[56:57], v[150:151]
	v_pk_mul_f32 v[40:41], v[40:41], v[150:151]
	s_nop 0
	v_mov_b32_dpp v152, v22 quad_perm:[1,0,3,2] row_mask:0xf bank_mask:0xf
	v_mov_b32_dpp v153, v6 quad_perm:[1,0,3,2] row_mask:0xf bank_mask:0xf
	v_mov_b32_dpp v154, v54 quad_perm:[1,0,3,2] row_mask:0xf bank_mask:0xf
	v_mov_b32_dpp v155, v38 quad_perm:[1,0,3,2] row_mask:0xf bank_mask:0xf
	v_cvt_pk_bf16_f32 v22, v22, v152
	v_cvt_pk_bf16_f32 v6, v6, v153
	v_cvt_pk_bf16_f32 v54, v54, v154
	v_cvt_pk_bf16_f32 v38, v38, v155
	v_mov_b32_dpp v152, v23 quad_perm:[1,0,3,2] row_mask:0xf bank_mask:0xf
	v_mov_b32_dpp v153, v7 quad_perm:[1,0,3,2] row_mask:0xf bank_mask:0xf
	v_mov_b32_dpp v154, v55 quad_perm:[1,0,3,2] row_mask:0xf bank_mask:0xf
	v_mov_b32_dpp v155, v39 quad_perm:[1,0,3,2] row_mask:0xf bank_mask:0xf
	v_cvt_pk_bf16_f32 v23, v23, v152
	v_cvt_pk_bf16_f32 v7, v7, v153
	v_cvt_pk_bf16_f32 v55, v55, v154
	v_cvt_pk_bf16_f32 v39, v39, v155
	v_mov_b32_dpp v152, v24 quad_perm:[1,0,3,2] row_mask:0xf bank_mask:0xf
	v_mov_b32_dpp v153, v8 quad_perm:[1,0,3,2] row_mask:0xf bank_mask:0xf
	v_mov_b32_dpp v154, v56 quad_perm:[1,0,3,2] row_mask:0xf bank_mask:0xf
	v_mov_b32_dpp v155, v40 quad_perm:[1,0,3,2] row_mask:0xf bank_mask:0xf
	v_cvt_pk_bf16_f32 v24, v24, v152
	v_cvt_pk_bf16_f32 v8, v8, v153
	v_cvt_pk_bf16_f32 v56, v56, v154
	v_cvt_pk_bf16_f32 v40, v40, v155
	v_mov_b32_dpp v152, v25 quad_perm:[1,0,3,2] row_mask:0xf bank_mask:0xf
	v_mov_b32_dpp v153, v9 quad_perm:[1,0,3,2] row_mask:0xf bank_mask:0xf
	v_mov_b32_dpp v154, v57 quad_perm:[1,0,3,2] row_mask:0xf bank_mask:0xf
	v_mov_b32_dpp v155, v41 quad_perm:[1,0,3,2] row_mask:0xf bank_mask:0xf
	v_cvt_pk_bf16_f32 v25, v25, v152
	v_cvt_pk_bf16_f32 v9, v9, v153
	v_cvt_pk_bf16_f32 v57, v57, v154
	v_cvt_pk_bf16_f32 v41, v41, v155
	ds_read_u16 v140, v138 offset:4096
	ds_read_u16 v141, v138 offset:4160
	ds_read_u16 v142, v138 offset:4224
	ds_read_u16 v143, v138 offset:4288
	ds_read_u16 v144, v138 offset:4352
	ds_read_u16 v145, v138 offset:4416
	ds_read_u16 v146, v138 offset:4480
	ds_read_u16 v147, v138 offset:4544
	ds_read_u16 v156, v138 offset:4608
	ds_read_u16 v157, v138 offset:4672
	ds_read_u16 v158, v138 offset:4736
	ds_read_u16 v159, v138 offset:4800
	ds_read_u16 v160, v138 offset:4864
	ds_read_u16 v161, v138 offset:4928
	ds_read_u16 v130, v138 offset:4992
	ds_read_u16 v131, v138 offset:5056
	v_pk_add_f32 v[26:27], v[26:27], v[118:119]
	v_pk_add_f32 v[10:11], v[10:11], v[118:119]
	v_pk_add_f32 v[58:59], v[58:59], v[118:119]
	v_pk_add_f32 v[42:43], v[42:43], v[118:119]
	v_pk_add_f32 v[28:29], v[28:29], v[120:121]
	v_pk_add_f32 v[12:13], v[12:13], v[120:121]
	v_pk_add_f32 v[60:61], v[60:61], v[120:121]
	v_pk_add_f32 v[44:45], v[44:45], v[120:121]
	s_waitcnt lgkmcnt(0)
	v_lshlrev_b32_e32 v140, 16, v140
	v_lshlrev_b32_e32 v141, 16, v141
	v_lshlrev_b32_e32 v142, 16, v142
	v_lshlrev_b32_e32 v143, 16, v143
	v_lshlrev_b32_e32 v144, 16, v144
	v_lshlrev_b32_e32 v145, 16, v145
	v_lshlrev_b32_e32 v146, 16, v146
	v_lshlrev_b32_e32 v147, 16, v147
	v_lshlrev_b32_e32 v156, 16, v156
	v_lshlrev_b32_e32 v157, 16, v157
	v_lshlrev_b32_e32 v158, 16, v158
	v_lshlrev_b32_e32 v159, 16, v159
	v_lshlrev_b32_e32 v160, 16, v160
	v_lshlrev_b32_e32 v161, 16, v161
	v_lshlrev_b32_e32 v130, 16, v130
	v_lshlrev_b32_e32 v131, 16, v131
	v_mul_f32_e32 v26, v26, v140
	v_mul_f32_e32 v10, v10, v141
	v_mul_f32_e32 v58, v58, v142
	v_mul_f32_e32 v42, v42, v143
	v_mul_f32_e32 v27, v27, v144
	v_mul_f32_e32 v11, v11, v145
	v_mul_f32_e32 v59, v59, v146
	v_mul_f32_e32 v43, v43, v147
	v_mul_f32_e32 v28, v28, v156
	v_mul_f32_e32 v12, v12, v157
	v_mul_f32_e32 v60, v60, v158
	v_mul_f32_e32 v44, v44, v159
	v_mul_f32_e32 v29, v29, v160
	v_mul_f32_e32 v13, v13, v161
	v_mul_f32_e32 v61, v61, v130
	v_mul_f32_e32 v45, v45, v131
	v_pk_mul_f32 v[148:149], v[26:27], v[26:27]
	v_pk_mul_f32 v[150:151], v[28:29], v[28:29]
	v_pk_fma_f32 v[148:149], v[10:11], v[10:11], v[148:149]
	v_pk_fma_f32 v[150:151], v[12:13], v[12:13], v[150:151]
	v_pk_fma_f32 v[148:149], v[58:59], v[58:59], v[148:149]
	v_pk_fma_f32 v[150:151], v[60:61], v[60:61], v[150:151]
	v_pk_fma_f32 v[148:149], v[42:43], v[42:43], v[148:149]
	v_pk_fma_f32 v[150:151], v[44:45], v[44:45], v[150:151]
	s_nop 1
	v_add_f32_dpp v148, v148, v148 quad_perm:[1,0,3,2] row_mask:0xf bank_mask:0xf
	v_add_f32_dpp v149, v149, v149 quad_perm:[1,0,3,2] row_mask:0xf bank_mask:0xf
	v_add_f32_dpp v150, v150, v150 quad_perm:[1,0,3,2] row_mask:0xf bank_mask:0xf
	v_add_f32_dpp v151, v151, v151 quad_perm:[1,0,3,2] row_mask:0xf bank_mask:0xf
	v_add_f32_dpp v148, v148, v148 quad_perm:[2,3,0,1] row_mask:0xf bank_mask:0xf
	v_add_f32_dpp v149, v149, v149 quad_perm:[2,3,0,1] row_mask:0xf bank_mask:0xf
	v_add_f32_dpp v150, v150, v150 quad_perm:[2,3,0,1] row_mask:0xf bank_mask:0xf
	v_add_f32_dpp v151, v151, v151 quad_perm:[2,3,0,1] row_mask:0xf bank_mask:0xf
	v_add_f32_dpp v148, v148, v148 row_half_mirror row_mask:0xf bank_mask:0xf
	v_add_f32_dpp v149, v149, v149 row_half_mirror row_mask:0xf bank_mask:0xf
	v_add_f32_dpp v150, v150, v150 row_half_mirror row_mask:0xf bank_mask:0xf
	v_add_f32_dpp v151, v151, v151 row_half_mirror row_mask:0xf bank_mask:0xf
	v_add_f32_dpp v148, v148, v148 row_mirror row_mask:0xf bank_mask:0xf
	v_add_f32_dpp v149, v149, v149 row_mirror row_mask:0xf bank_mask:0xf
	v_add_f32_dpp v150, v150, v150 row_mirror row_mask:0xf bank_mask:0xf
	v_add_f32_dpp v151, v151, v151 row_mirror row_mask:0xf bank_mask:0xf
	v_mov_b32_e32 v152, v148
	v_mov_b32_e32 v153, v149
	v_mov_b32_e32 v154, v150
	v_mov_b32_e32 v155, v151
	v_permlane16_swap_b32_e32 v148, v152
; __device__ __forceinline__ float bf2f(unsigned h) { return __uint_as_float(h << 16); }
; __device__ __forceinline__ unsigned cvt_pk_bf16(float lo, float hi) { unsigned r; asm volatile("v_cvt_pk_bf16_f32 %0, %1, %2" : "=v"(r) : "v"(lo), "v"(hi)); return r; }
; __device__ __forceinline__ int crow(int r, int hi) { return (r & 3) + 8 * (r >> 2) + 4 * hi; }
; __device__ __forceinline__ void gmlp_phase(const bf16_t* GU, const bf16_t* GV, const float* lng, const float* lnb, const float* wsp, const float* bsp, bf16_t* Y, lptr lds, int blk, int G, int tid_) {
;     ...
; #pragma unroll
;         for (int r = 0; r < 16; ++r) { const int tr = crow(r, hi); const float bt = btv[r];
;             float v0 = bf2f(up[tr * HD]) * (acc[0][r] + bt), v1 = bf2f(up[tr * HD + 32]) * (acc[1][r] + bt), v2 = bf2f(up[tr * HD + 64]) * (acc[2][r] + bt), v3 = bf2f(up[tr * HD + 96]) * (acc[3][r] + bt);
;             float ss = (v0 * v0 + v1 * v1) + (v2 * v2 + v3 * v3);
;             ss += __shfl_xor(ss, 1); ss += __shfl_xor(ss, 2); ss += __shfl_xor(ss, 4); ss += __shfl_xor(ss, 8); ss += __shfl_xor(ss, 16);
;             const float rs = rsqrtf(ss * (1.0f / 128.0f) + EPS);
;             v0 *= rs; v1 *= rs; v2 *= rs; v3 *= rs;
;             const float n0 = __shfl_xor(v0, 1), n1 = __shfl_xor(v1, 1), n2 = __shfl_xor(v2, 1), n3 = __shfl_xor(v3, 1);
;             if ((r32 & 1) == 0) { bf16_t* op = yp + (size_t)tr * DM;
;                 *(unsigned*)(op) = cvt_pk_bf16(v0, n0); *(unsigned*)(op + 32) = cvt_pk_bf16(v1, n1); *(unsigned*)(op + 64) = cvt_pk_bf16(v2, n2); *(unsigned*)(op + 96) = cvt_pk_bf16(v3, n3); } }
	v_permlane16_swap_b32_e32 v149, v153
	v_permlane16_swap_b32_e32 v150, v154
	v_permlane16_swap_b32_e32 v151, v155
	v_add_f32_e32 v148, v148, v152
	v_add_f32_e32 v149, v149, v153
	v_add_f32_e32 v150, v150, v154
	v_add_f32_e32 v151, v151, v155
	v_fmamk_f32 v148, v148, 0x3c000000, v192
	v_fmamk_f32 v149, v149, 0x3c000000, v192
	v_fmamk_f32 v150, v150, 0x3c000000, v192
	v_fmamk_f32 v151, v151, 0x3c000000, v192
	v_rsq_f32_e32 v148, v148
	v_rsq_f32_e32 v149, v149
	v_rsq_f32_e32 v150, v150
	v_rsq_f32_e32 v151, v151
	s_nop 0
	v_pk_mul_f32 v[26:27], v[26:27], v[148:149]
	v_pk_mul_f32 v[10:11], v[10:11], v[148:149]
	v_pk_mul_f32 v[58:59], v[58:59], v[148:149]
	v_pk_mul_f32 v[42:43], v[42:43], v[148:149]
	v_pk_mul_f32 v[28:29], v[28:29], v[150:151]
	v_pk_mul_f32 v[12:13], v[12:13], v[150:151]
	v_pk_mul_f32 v[60:61], v[60:61], v[150:151]
	v_pk_mul_f32 v[44:45], v[44:45], v[150:151]
	s_nop 0
	v_mov_b32_dpp v152, v26 quad_perm:[1,0,3,2] row_mask:0xf bank_mask:0xf
	v_mov_b32_dpp v153, v10 quad_perm:[1,0,3,2] row_mask:0xf bank_mask:0xf
	v_mov_b32_dpp v154, v58 quad_perm:[1,0,3,2] row_mask:0xf bank_mask:0xf
	v_mov_b32_dpp v155, v42 quad_perm:[1,0,3,2] row_mask:0xf bank_mask:0xf
	v_cvt_pk_bf16_f32 v26, v26, v152
	v_cvt_pk_bf16_f32 v10, v10, v153
	v_cvt_pk_bf16_f32 v58, v58, v154
	v_cvt_pk_bf16_f32 v42, v42, v155
	v_mov_b32_dpp v152, v27 quad_perm:[1,0,3,2] row_mask:0xf bank_mask:0xf
	v_mov_b32_dpp v153, v11 quad_perm:[1,0,3,2] row_mask:0xf bank_mask:0xf
	v_mov_b32_dpp v154, v59 quad_perm:[1,0,3,2] row_mask:0xf bank_mask:0xf
	v_mov_b32_dpp v155, v43 quad_perm:[1,0,3,2] row_mask:0xf bank_mask:0xf
	v_cvt_pk_bf16_f32 v27, v27, v152
	v_cvt_pk_bf16_f32 v11, v11, v153
	v_cvt_pk_bf16_f32 v59, v59, v154
	v_cvt_pk_bf16_f32 v43, v43, v155
	v_mov_b32_dpp v152, v28 quad_perm:[1,0,3,2] row_mask:0xf bank_mask:0xf
	v_mov_b32_dpp v153, v12 quad_perm:[1,0,3,2] row_mask:0xf bank_mask:0xf
	v_mov_b32_dpp v154, v60 quad_perm:[1,0,3,2] row_mask:0xf bank_mask:0xf
	v_mov_b32_dpp v155, v44 quad_perm:[1,0,3,2] row_mask:0xf bank_mask:0xf
	v_cvt_pk_bf16_f32 v28, v28, v152
	v_cvt_pk_bf16_f32 v12, v12, v153
	v_cvt_pk_bf16_f32 v60, v60, v154
	v_cvt_pk_bf16_f32 v44, v44, v155
	v_mov_b32_dpp v152, v29 quad_perm:[1,0,3,2] row_mask:0xf bank_mask:0xf
	v_mov_b32_dpp v153, v13 quad_perm:[1,0,3,2] row_mask:0xf bank_mask:0xf
	v_mov_b32_dpp v154, v61 quad_perm:[1,0,3,2] row_mask:0xf bank_mask:0xf
	v_mov_b32_dpp v155, v45 quad_perm:[1,0,3,2] row_mask:0xf bank_mask:0xf
	v_cvt_pk_bf16_f32 v29, v29, v152
	v_cvt_pk_bf16_f32 v13, v13, v153
	v_cvt_pk_bf16_f32 v61, v61, v154
	v_cvt_pk_bf16_f32 v45, v45, v155
	ds_read_u16 v140, v138 offset:6144
	ds_read_u16 v141, v138 offset:6208
	ds_read_u16 v142, v138 offset:6272
	ds_read_u16 v143, v138 offset:6336
	ds_read_u16 v144, v138 offset:6400
	ds_read_u16 v145, v138 offset:6464
	ds_read_u16 v146, v138 offset:6528
	ds_read_u16 v147, v138 offset:6592
	ds_read_u16 v156, v138 offset:6656
	ds_read_u16 v157, v138 offset:6720
	ds_read_u16 v158, v138 offset:6784
	ds_read_u16 v159, v138 offset:6848
	ds_read_u16 v160, v138 offset:6912
	ds_read_u16 v161, v138 offset:6976
	ds_read_u16 v130, v138 offset:7040
	ds_read_u16 v131, v138 offset:7104
	v_pk_add_f32 v[30:31], v[30:31], v[114:115]
	v_pk_add_f32 v[14:15], v[14:15], v[114:115]
	v_pk_add_f32 v[62:63], v[62:63], v[114:115]
	v_pk_add_f32 v[46:47], v[46:47], v[114:115]
	v_pk_add_f32 v[32:33], v[32:33], v[116:117]
	v_pk_add_f32 v[16:17], v[16:17], v[116:117]
	v_pk_add_f32 v[64:65], v[64:65], v[116:117]
	v_pk_add_f32 v[48:49], v[48:49], v[116:117]
	s_waitcnt lgkmcnt(0)
	v_lshlrev_b32_e32 v140, 16, v140
	v_lshlrev_b32_e32 v141, 16, v141
	v_lshlrev_b32_e32 v142, 16, v142
	v_lshlrev_b32_e32 v143, 16, v143
	v_lshlrev_b32_e32 v144, 16, v144
	v_lshlrev_b32_e32 v145, 16, v145
	v_lshlrev_b32_e32 v146, 16, v146
	v_lshlrev_b32_e32 v147, 16, v147
	v_lshlrev_b32_e32 v156, 16, v156
	v_lshlrev_b32_e32 v157, 16, v157
	v_lshlrev_b32_e32 v158, 16, v158
	v_lshlrev_b32_e32 v159, 16, v159
	v_lshlrev_b32_e32 v160, 16, v160
	v_lshlrev_b32_e32 v161, 16, v161
	v_lshlrev_b32_e32 v130, 16, v130
	v_lshlrev_b32_e32 v131, 16, v131
	v_mul_f32_e32 v30, v30, v140
	v_mul_f32_e32 v14, v14, v141
	v_mul_f32_e32 v62, v62, v142
	v_mul_f32_e32 v46, v46, v143
	v_mul_f32_e32 v31, v31, v144
	v_mul_f32_e32 v15, v15, v145
	v_mul_f32_e32 v63, v63, v146
	v_mul_f32_e32 v47, v47, v147
	v_mul_f32_e32 v32, v32, v156
	v_mul_f32_e32 v16, v16, v157
	v_mul_f32_e32 v64, v64, v158
	v_mul_f32_e32 v48, v48, v159
	v_mul_f32_e32 v33, v33, v160
	v_mul_f32_e32 v17, v17, v161
	v_mul_f32_e32 v65, v65, v130
	v_mul_f32_e32 v49, v49, v131
	v_pk_mul_f32 v[148:149], v[30:31], v[30:31]
	v_pk_mul_f32 v[150:151], v[32:33], v[32:33]
	v_pk_fma_f32 v[148:149], v[14:15], v[14:15], v[148:149]
	v_pk_fma_f32 v[150:151], v[16:17], v[16:17], v[150:151]
	v_pk_fma_f32 v[148:149], v[62:63], v[62:63], v[148:149]
	v_pk_fma_f32 v[150:151], v[64:65], v[64:65], v[150:151]
	v_pk_fma_f32 v[148:149], v[46:47], v[46:47], v[148:149]
	v_pk_fma_f32 v[150:151], v[48:49], v[48:49], v[150:151]
	s_nop 1
	v_add_f32_dpp v148, v148, v148 quad_perm:[1,0,3,2] row_mask:0xf bank_mask:0xf
	v_add_f32_dpp v149, v149, v149 quad_perm:[1,0,3,2] row_mask:0xf bank_mask:0xf
	v_add_f32_dpp v150, v150, v150 quad_perm:[1,0,3,2] row_mask:0xf bank_mask:0xf
	v_add_f32_dpp v151, v151, v151 quad_perm:[1,0,3,2] row_mask:0xf bank_mask:0xf
	v_add_f32_dpp v148, v148, v148 quad_perm:[2,3,0,1] row_mask:0xf bank_mask:0xf
	v_add_f32_dpp v149, v149, v149 quad_perm:[2,3,0,1] row_mask:0xf bank_mask:0xf
	v_add_f32_dpp v150, v150, v150 quad_perm:[2,3,0,1] row_mask:0xf bank_mask:0xf
	v_add_f32_dpp v151, v151, v151 quad_perm:[2,3,0,1] row_mask:0xf bank_mask:0xf
; __device__ __forceinline__ float bf2f(unsigned h) { return __uint_as_float(h << 16); }
; __device__ __forceinline__ unsigned cvt_pk_bf16(float lo, float hi) { unsigned r; asm volatile("v_cvt_pk_bf16_f32 %0, %1, %2" : "=v"(r) : "v"(lo), "v"(hi)); return r; }
; __device__ __forceinline__ int crow(int r, int hi) { return (r & 3) + 8 * (r >> 2) + 4 * hi; }
; __device__ __forceinline__ void gmlp_phase(const bf16_t* GU, const bf16_t* GV, const float* lng, const float* lnb, const float* wsp, const float* bsp, bf16_t* Y, lptr lds, int blk, int G, int tid_) {
;     ...
; #pragma unroll
;         for (int r = 0; r < 16; ++r) { const int tr = crow(r, hi); const float bt = btv[r];
;             float v0 = bf2f(up[tr * HD]) * (acc[0][r] + bt), v1 = bf2f(up[tr * HD + 32]) * (acc[1][r] + bt), v2 = bf2f(up[tr * HD + 64]) * (acc[2][r] + bt), v3 = bf2f(up[tr * HD + 96]) * (acc[3][r] + bt);
;             float ss = (v0 * v0 + v1 * v1) + (v2 * v2 + v3 * v3);
;             ss += __shfl_xor(ss, 1); ss += __shfl_xor(ss, 2); ss += __shfl_xor(ss, 4); ss += __shfl_xor(ss, 8); ss += __shfl_xor(ss, 16);
;             const float rs = rsqrtf(ss * (1.0f / 128.0f) + EPS);
;             v0 *= rs; v1 *= rs; v2 *= rs; v3 *= rs;
;             const float n0 = __shfl_xor(v0, 1), n1 = __shfl_xor(v1, 1), n2 = __shfl_xor(v2, 1), n3 = __shfl_xor(v3, 1);
;             if ((r32 & 1) == 0) { bf16_t* op = yp + (size_t)tr * DM;
;                 *(unsigned*)(op) = cvt_pk_bf16(v0, n0); *(unsigned*)(op + 32) = cvt_pk_bf16(v1, n1); *(unsigned*)(op + 64) = cvt_pk_bf16(v2, n2); *(unsigned*)(op + 96) = cvt_pk_bf16(v3, n3); } }
	v_add_f32_dpp v148, v148, v148 row_half_mirror row_mask:0xf bank_mask:0xf
	v_add_f32_dpp v149, v149, v149 row_half_mirror row_mask:0xf bank_mask:0xf
	v_add_f32_dpp v150, v150, v150 row_half_mirror row_mask:0xf bank_mask:0xf
	v_add_f32_dpp v151, v151, v151 row_half_mirror row_mask:0xf bank_mask:0xf
	v_add_f32_dpp v148, v148, v148 row_mirror row_mask:0xf bank_mask:0xf
	v_add_f32_dpp v149, v149, v149 row_mirror row_mask:0xf bank_mask:0xf
	v_add_f32_dpp v150, v150, v150 row_mirror row_mask:0xf bank_mask:0xf
	v_add_f32_dpp v151, v151, v151 row_mirror row_mask:0xf bank_mask:0xf
	v_mov_b32_e32 v152, v148
	v_mov_b32_e32 v153, v149
	v_mov_b32_e32 v154, v150
	v_mov_b32_e32 v155, v151
	v_permlane16_swap_b32_e32 v148, v152
	v_permlane16_swap_b32_e32 v149, v153
	v_permlane16_swap_b32_e32 v150, v154
	v_permlane16_swap_b32_e32 v151, v155
	v_add_f32_e32 v148, v148, v152
	v_add_f32_e32 v149, v149, v153
	v_add_f32_e32 v150, v150, v154
	v_add_f32_e32 v151, v151, v155
	v_fmamk_f32 v148, v148, 0x3c000000, v192
	v_fmamk_f32 v149, v149, 0x3c000000, v192
	v_fmamk_f32 v150, v150, 0x3c000000, v192
	v_fmamk_f32 v151, v151, 0x3c000000, v192
	v_rsq_f32_e32 v148, v148
	v_rsq_f32_e32 v149, v149
	v_rsq_f32_e32 v150, v150
	v_rsq_f32_e32 v151, v151
	s_nop 0
	v_pk_mul_f32 v[30:31], v[30:31], v[148:149]
	v_pk_mul_f32 v[14:15], v[14:15], v[148:149]
	v_pk_mul_f32 v[62:63], v[62:63], v[148:149]
	v_pk_mul_f32 v[46:47], v[46:47], v[148:149]
	v_pk_mul_f32 v[32:33], v[32:33], v[150:151]
	v_pk_mul_f32 v[16:17], v[16:17], v[150:151]
	v_pk_mul_f32 v[64:65], v[64:65], v[150:151]
	v_pk_mul_f32 v[48:49], v[48:49], v[150:151]
	s_nop 0
	v_mov_b32_dpp v152, v30 quad_perm:[1,0,3,2] row_mask:0xf bank_mask:0xf
	v_mov_b32_dpp v153, v14 quad_perm:[1,0,3,2] row_mask:0xf bank_mask:0xf
	v_mov_b32_dpp v154, v62 quad_perm:[1,0,3,2] row_mask:0xf bank_mask:0xf
	v_mov_b32_dpp v155, v46 quad_perm:[1,0,3,2] row_mask:0xf bank_mask:0xf
	v_cvt_pk_bf16_f32 v30, v30, v152
	v_cvt_pk_bf16_f32 v14, v14, v153
	v_cvt_pk_bf16_f32 v62, v62, v154
	v_cvt_pk_bf16_f32 v46, v46, v155
	v_mov_b32_dpp v152, v31 quad_perm:[1,0,3,2] row_mask:0xf bank_mask:0xf
	v_mov_b32_dpp v153, v15 quad_perm:[1,0,3,2] row_mask:0xf bank_mask:0xf
	v_mov_b32_dpp v154, v63 quad_perm:[1,0,3,2] row_mask:0xf bank_mask:0xf
	v_mov_b32_dpp v155, v47 quad_perm:[1,0,3,2] row_mask:0xf bank_mask:0xf
	v_cvt_pk_bf16_f32 v31, v31, v152
	v_cvt_pk_bf16_f32 v15, v15, v153
	v_cvt_pk_bf16_f32 v63, v63, v154
	v_cvt_pk_bf16_f32 v47, v47, v155
	v_mov_b32_dpp v152, v32 quad_perm:[1,0,3,2] row_mask:0xf bank_mask:0xf
	v_mov_b32_dpp v153, v16 quad_perm:[1,0,3,2] row_mask:0xf bank_mask:0xf
	v_mov_b32_dpp v154, v64 quad_perm:[1,0,3,2] row_mask:0xf bank_mask:0xf
	v_mov_b32_dpp v155, v48 quad_perm:[1,0,3,2] row_mask:0xf bank_mask:0xf
	v_cvt_pk_bf16_f32 v32, v32, v152
	v_cvt_pk_bf16_f32 v16, v16, v153
	v_cvt_pk_bf16_f32 v64, v64, v154
	v_cvt_pk_bf16_f32 v48, v48, v155
	v_mov_b32_dpp v152, v33 quad_perm:[1,0,3,2] row_mask:0xf bank_mask:0xf
	v_mov_b32_dpp v153, v17 quad_perm:[1,0,3,2] row_mask:0xf bank_mask:0xf
	v_mov_b32_dpp v154, v65 quad_perm:[1,0,3,2] row_mask:0xf bank_mask:0xf
	v_mov_b32_dpp v155, v49 quad_perm:[1,0,3,2] row_mask:0xf bank_mask:0xf
	v_cvt_pk_bf16_f32 v33, v33, v152
	v_cvt_pk_bf16_f32 v17, v17, v153
	v_cvt_pk_bf16_f32 v65, v65, v154
	v_cvt_pk_bf16_f32 v49, v49, v155
	s_mov_b64 exec, vcc
	ds_write_b32 v138, v18
	ds_write_b32 v138, v2 offset:64
	ds_write_b32 v138, v50 offset:128
	ds_write_b32 v138, v34 offset:192
	ds_write_b32 v138, v19 offset:256
	ds_write_b32 v138, v3 offset:320
	ds_write_b32 v138, v51 offset:384
	ds_write_b32 v138, v35 offset:448
	ds_write_b32 v138, v20 offset:512
	ds_write_b32 v138, v4 offset:576
	ds_write_b32 v138, v52 offset:640
	ds_write_b32 v138, v36 offset:704
	ds_write_b32 v138, v21 offset:768
	ds_write_b32 v138, v5 offset:832
	ds_write_b32 v138, v53 offset:896
	ds_write_b32 v138, v37 offset:960
	ds_write_b32 v138, v22 offset:2048
	ds_write_b32 v138, v6 offset:2112
	ds_write_b32 v138, v54 offset:2176
	ds_write_b32 v138, v38 offset:2240
	ds_write_b32 v138, v23 offset:2304
	ds_write_b32 v138, v7 offset:2368
	ds_write_b32 v138, v55 offset:2432
	ds_write_b32 v138, v39 offset:2496
	ds_write_b32 v138, v24 offset:2560
	ds_write_b32 v138, v8 offset:2624
	ds_write_b32 v138, v56 offset:2688
	ds_write_b32 v138, v40 offset:2752
	ds_write_b32 v138, v25 offset:2816
	ds_write_b32 v138, v9 offset:2880
	ds_write_b32 v138, v57 offset:2944
	ds_write_b32 v138, v41 offset:3008
	ds_write_b32 v138, v26 offset:4096
	ds_write_b32 v138, v10 offset:4160
	ds_write_b32 v138, v58 offset:4224
	ds_write_b32 v138, v42 offset:4288
	ds_write_b32 v138, v27 offset:4352
	ds_write_b32 v138, v11 offset:4416
	ds_write_b32 v138, v59 offset:4480
	ds_write_b32 v138, v43 offset:4544
	ds_write_b32 v138, v28 offset:4608
	ds_write_b32 v138, v12 offset:4672
	ds_write_b32 v138, v60 offset:4736
	ds_write_b32 v138, v44 offset:4800
	ds_write_b32 v138, v29 offset:4864
	ds_write_b32 v138, v13 offset:4928
	ds_write_b32 v138, v61 offset:4992
	ds_write_b32 v138, v45 offset:5056
	ds_write_b32 v138, v30 offset:6144
	ds_write_b32 v138, v14 offset:6208
	ds_write_b32 v138, v62 offset:6272
	ds_write_b32 v138, v46 offset:6336
	ds_write_b32 v138, v31 offset:6400
	ds_write_b32 v138, v15 offset:6464
	ds_write_b32 v138, v63 offset:6528
	ds_write_b32 v138, v47 offset:6592
	ds_write_b32 v138, v32 offset:6656
	ds_write_b32 v138, v16 offset:6720
	ds_write_b32 v138, v64 offset:6784
	ds_write_b32 v138, v48 offset:6848
	ds_write_b32 v138, v33 offset:6912
	ds_write_b32 v138, v17 offset:6976
	ds_write_b32 v138, v65 offset:7040
	ds_write_b32 v138, v49 offset:7104
	s_mov_b64 exec, -1
	v_subrev_u32_e32 v148, s30, v138
	v_and_b32_e32 v149, 63, v148
	v_lshrrev_b32_e32 v150, 10, v148
	v_lshlrev_b32_e32 v151, 3, v149
	v_lshrrev_b32_e32 v152, 5, v149
	v_and_b32_e32 v153, 31, v149
	v_lshl_add_u32 v151, v150, 9, v151
	v_lshl_add_u32 v152, v150, 1, v152
	v_lshlrev_b32_e32 v153, 3, v153
	v_add_u32_e32 v151, s30, v151
	v_lshl_add_u32 v162, v152, 12, v153
	ds_read_b128 v[4:7], v151
	ds_read_b128 v[8:11], v151 offset:1024
	ds_read_b128 v[12:15], v151 offset:2048
	ds_read_b128 v[16:19], v151 offset:3072
	ds_read_b128 v[20:23], v151 offset:4096
	ds_read_b128 v[24:27], v151 offset:5120
	ds_read_b128 v[28:31], v151 offset:6144
	ds_read_b128 v[32:35], v151 offset:7168
	s_waitcnt lgkmcnt(7)
; __device__ __forceinline__ unsigned cvt_pk_bf16(float lo, float hi) { unsigned r; asm volatile("v_cvt_pk_bf16_f32 %0, %1, %2" : "=v"(r) : "v"(lo), "v"(hi)); return r; }
; __device__ __forceinline__ void gmlp_phase(const bf16_t* GU, const bf16_t* GV, const float* lng, const float* lnb, const float* wsp, const float* bsp, bf16_t* Y, lptr lds, int blk, int G, int tid_) {
;     ...
;             if ((r32 & 1) == 0) { bf16_t* op = yp + (size_t)tr * DM;
;                 *(unsigned*)(op) = cvt_pk_bf16(v0, n0); *(unsigned*)(op + 32) = cvt_pk_bf16(v1, n1); *(unsigned*)(op + 64) = cvt_pk_bf16(v2, n2); *(unsigned*)(op + 96) = cvt_pk_bf16(v3, n3); } }
	global_store_dwordx4 v162, v[4:7], s[4:5]
	s_add_u32 s4, s4, 0x4000
	s_addc_u32 s5, s5, 0
	s_waitcnt lgkmcnt(6)
	global_store_dwordx4 v162, v[8:11], s[4:5]
	s_add_u32 s4, s4, 0x4000
	s_addc_u32 s5, s5, 0
	s_waitcnt lgkmcnt(5)
	global_store_dwordx4 v162, v[12:15], s[4:5]
	s_add_u32 s4, s4, 0x4000
	s_addc_u32 s5, s5, 0
	s_waitcnt lgkmcnt(4)
	global_store_dwordx4 v162, v[16:19], s[4:5]
	s_add_u32 s4, s4, 0x4000
	s_addc_u32 s5, s5, 0
	s_waitcnt lgkmcnt(3)
	global_store_dwordx4 v162, v[20:23], s[4:5]
	s_add_u32 s4, s4, 0x4000
	s_addc_u32 s5, s5, 0
	s_waitcnt lgkmcnt(2)
	global_store_dwordx4 v162, v[24:27], s[4:5]
	s_add_u32 s4, s4, 0x4000
	s_addc_u32 s5, s5, 0
	s_waitcnt lgkmcnt(1)
	global_store_dwordx4 v162, v[28:31], s[4:5]
	s_add_u32 s4, s4, 0x4000
	s_addc_u32 s5, s5, 0
	s_waitcnt lgkmcnt(0)
	global_store_dwordx4 v162, v[32:35], s[4:5]
	s_mov_b64 exec, -1
	s_mov_b64 s[4:5], -1
	s_branch .LBB0_603

; #define LAS __attribute__((address_space(3)))
; __device__ __forceinline__ float bf2f(unsigned h) { return __uint_as_float(h << 16); }
; __device__ __forceinline__ unsigned cvt_pk_bf16(float lo, float hi) { unsigned r; asm volatile("v_cvt_pk_bf16_f32 %0, %1, %2" : "=v"(r) : "v"(lo), "v"(hi)); return r; }
; __device__ __forceinline__ int crow(int r, int hi) { return (r & 3) + 8 * (r >> 2) + 4 * hi; }
; __device__ __forceinline__ void retout_phase(const bf16_t* RQ, const bf16_t* RK, const bf16_t* RV, const bf16_t* RG, const bf16_t* ST, bf16_t* Y, lptr lds, int blk, int G, int tid_) {
;     ...
;         const LAS bf16_t* gp = (const LAS bf16_t*)(lds + ci * 32768 + 16384 + (32 * tb) * 256) + r32; bf16_t* yp = Y + ((size_t)(b * SEQ + n * 64 + 32 * tb)) * DM + 1024 + hr * HD + r32;
; #pragma unroll
;         for (int r = 0; r < 16; ++r) { const int tr = crow(r, hi);
;             float v0 = o[0][r], v1 = o[1][r], v2 = o[2][r], v3 = o[3][r];
;             float ss = (v0 * v0 + v1 * v1) + (v2 * v2 + v3 * v3);
;             ss += __shfl_xor(ss, 1); ss += __shfl_xor(ss, 2); ss += __shfl_xor(ss, 4); ss += __shfl_xor(ss, 8); ss += __shfl_xor(ss, 16);
;             const float rs = rsqrtf(ss * (1.0f / 128.0f) + EPS);
;             v0 *= rs * bf2f(gp[tr * HD]); v1 *= rs * bf2f(gp[tr * HD + 32]); v2 *= rs * bf2f(gp[tr * HD + 64]); v3 *= rs * bf2f(gp[tr * HD + 96]);
;             const float n0 = __shfl_xor(v0, 1), n1 = __shfl_xor(v1, 1), n2 = __shfl_xor(v2, 1), n3 = __shfl_xor(v3, 1);
;             if ((r32 & 1) == 0) { bf16_t* op = yp + (size_t)tr * DM;
;                 *(unsigned*)(op) = cvt_pk_bf16(v0, n0); *(unsigned*)(op + 32) = cvt_pk_bf16(v1, n1); *(unsigned*)(op + 64) = cvt_pk_bf16(v2, n2); *(unsigned*)(op + 96) = cvt_pk_bf16(v3, n3); } }
.LBB0_788:
	s_lshl_b32 s4, s26, 13
	s_add_i32 s27, s27, s4
	s_and_b32 s4, s20, 0xfffff000
	s_add_i32 s25, s25, s4
	s_or_b32 s4, s25, s28
	s_ashr_i32 s5, s4, 31
	s_lshl_b64 s[4:5], s[4:5], 12
	s_add_u32 s4, s16, s4
	s_addc_u32 s5, s17, s5
	s_lshl_b32 s12, s24, 8
	s_add_u32 s4, s4, s12
	s_addc_u32 s5, s5, 0
	s_add_u32 s4, s4, 0x39800800
	s_addc_u32 s5, s5, 0
	v_lshlrev_b32_e32 v162, 1, v123
	v_cmp_eq_u32_e32 vcc, 0, v122
	v_add_u32_e32 v78, s27, v162
	v_lshl_add_u32 v78, v124, 10, v78
	v_pk_mul_f32 v[66:67], v[2:3], v[2:3]
	v_pk_mul_f32 v[68:69], v[4:5], v[4:5]
	v_pk_fma_f32 v[66:67], v[18:19], v[18:19], v[66:67]
	v_pk_fma_f32 v[68:69], v[20:21], v[20:21], v[68:69]
	v_pk_fma_f32 v[66:67], v[34:35], v[34:35], v[66:67]
	v_pk_fma_f32 v[68:69], v[36:37], v[36:37], v[68:69]
	v_pk_fma_f32 v[66:67], v[50:51], v[50:51], v[66:67]
	v_pk_fma_f32 v[68:69], v[52:53], v[52:53], v[68:69]
	s_nop 1
	v_add_f32_dpp v66, v66, v66 quad_perm:[1,0,3,2] row_mask:0xf bank_mask:0xf
	v_add_f32_dpp v67, v67, v67 quad_perm:[1,0,3,2] row_mask:0xf bank_mask:0xf
	v_add_f32_dpp v68, v68, v68 quad_perm:[1,0,3,2] row_mask:0xf bank_mask:0xf
	v_add_f32_dpp v69, v69, v69 quad_perm:[1,0,3,2] row_mask:0xf bank_mask:0xf
	v_add_f32_dpp v66, v66, v66 quad_perm:[2,3,0,1] row_mask:0xf bank_mask:0xf
	v_add_f32_dpp v67, v67, v67 quad_perm:[2,3,0,1] row_mask:0xf bank_mask:0xf
	v_add_f32_dpp v68, v68, v68 quad_perm:[2,3,0,1] row_mask:0xf bank_mask:0xf
	v_add_f32_dpp v69, v69, v69 quad_perm:[2,3,0,1] row_mask:0xf bank_mask:0xf
	v_add_f32_dpp v66, v66, v66 row_half_mirror row_mask:0xf bank_mask:0xf
	v_add_f32_dpp v67, v67, v67 row_half_mirror row_mask:0xf bank_mask:0xf
	v_add_f32_dpp v68, v68, v68 row_half_mirror row_mask:0xf bank_mask:0xf
	v_add_f32_dpp v69, v69, v69 row_half_mirror row_mask:0xf bank_mask:0xf
	v_add_f32_dpp v66, v66, v66 row_mirror row_mask:0xf bank_mask:0xf
	v_add_f32_dpp v67, v67, v67 row_mirror row_mask:0xf bank_mask:0xf
	v_add_f32_dpp v68, v68, v68 row_mirror row_mask:0xf bank_mask:0xf
	v_add_f32_dpp v69, v69, v69 row_mirror row_mask:0xf bank_mask:0xf
	v_mov_b32_e32 v70, v66
	v_mov_b32_e32 v71, v67
	v_mov_b32_e32 v72, v68
	v_mov_b32_e32 v73, v69
	v_permlane16_swap_b32_e32 v66, v70
	v_permlane16_swap_b32_e32 v67, v71
	v_permlane16_swap_b32_e32 v68, v72
	v_permlane16_swap_b32_e32 v69, v73
	v_add_f32_e32 v66, v66, v70
	v_add_f32_e32 v67, v67, v71
	v_add_f32_e32 v68, v68, v72
	v_add_f32_e32 v69, v69, v73
	v_fmamk_f32 v66, v66, 0x3c000000, v192
	v_fmamk_f32 v67, v67, 0x3c000000, v192
	v_fmamk_f32 v68, v68, 0x3c000000, v192
	v_fmamk_f32 v69, v69, 0x3c000000, v192
	v_rsq_f32_e32 v66, v66
	v_rsq_f32_e32 v67, v67
	v_rsq_f32_e32 v68, v68
	v_rsq_f32_e32 v69, v69
	ds_read_u16 v74, v78 offset:16384
	ds_read_u16 v75, v78 offset:16448
	ds_read_u16 v76, v78 offset:16512
	ds_read_u16 v77, v78 offset:16576
	s_waitcnt lgkmcnt(0)
	v_lshlrev_b32_e32 v74, 16, v74
	v_lshlrev_b32_e32 v75, 16, v75
	v_lshlrev_b32_e32 v76, 16, v76
	v_lshlrev_b32_e32 v77, 16, v77
	v_mul_f32_e32 v74, v66, v74
	v_mul_f32_e32 v75, v66, v75
	v_mul_f32_e32 v76, v66, v76
	v_mul_f32_e32 v77, v66, v77
	v_mul_f32_e32 v2, v2, v74
	v_mul_f32_e32 v18, v18, v75
	v_mul_f32_e32 v34, v34, v76
	v_mul_f32_e32 v50, v50, v77
	s_nop 0
	v_mov_b32_dpp v70, v2 quad_perm:[1,0,3,2] row_mask:0xf bank_mask:0xf
	v_mov_b32_dpp v71, v18 quad_perm:[1,0,3,2] row_mask:0xf bank_mask:0xf
	v_mov_b32_dpp v72, v34 quad_perm:[1,0,3,2] row_mask:0xf bank_mask:0xf
	v_mov_b32_dpp v73, v50 quad_perm:[1,0,3,2] row_mask:0xf bank_mask:0xf
	v_cvt_pk_bf16_f32 v2, v2, v70
	v_cvt_pk_bf16_f32 v18, v18, v71
	v_cvt_pk_bf16_f32 v34, v34, v72
	v_cvt_pk_bf16_f32 v50, v50, v73
	ds_read_u16 v74, v78 offset:16640
	ds_read_u16 v75, v78 offset:16704
	ds_read_u16 v76, v78 offset:16768
	ds_read_u16 v77, v78 offset:16832
	s_waitcnt lgkmcnt(0)
	v_lshlrev_b32_e32 v74, 16, v74
	v_lshlrev_b32_e32 v75, 16, v75
	v_lshlrev_b32_e32 v76, 16, v76
	v_lshlrev_b32_e32 v77, 16, v77
	v_mul_f32_e32 v74, v67, v74
	v_mul_f32_e32 v75, v67, v75
	v_mul_f32_e32 v76, v67, v76
	v_mul_f32_e32 v77, v67, v77
	v_mul_f32_e32 v3, v3, v74
	v_mul_f32_e32 v19, v19, v75
	v_mul_f32_e32 v35, v35, v76
	v_mul_f32_e32 v51, v51, v77
	s_nop 0
	v_mov_b32_dpp v70, v3 quad_perm:[1,0,3,2] row_mask:0xf bank_mask:0xf
	v_mov_b32_dpp v71, v19 quad_perm:[1,0,3,2] row_mask:0xf bank_mask:0xf
	v_mov_b32_dpp v72, v35 quad_perm:[1,0,3,2] row_mask:0xf bank_mask:0xf
	v_mov_b32_dpp v73, v51 quad_perm:[1,0,3,2] row_mask:0xf bank_mask:0xf
	v_cvt_pk_bf16_f32 v3, v3, v70
	v_cvt_pk_bf16_f32 v19, v19, v71
	v_cvt_pk_bf16_f32 v35, v35, v72
	v_cvt_pk_bf16_f32 v51, v51, v73
	ds_read_u16 v74, v78 offset:16896
	ds_read_u16 v75, v78 offset:16960
	ds_read_u16 v76, v78 offset:17024
	ds_read_u16 v77, v78 offset:17088
	s_waitcnt lgkmcnt(0)
	v_lshlrev_b32_e32 v74, 16, v74
	v_lshlrev_b32_e32 v75, 16, v75
	v_lshlrev_b32_e32 v76, 16, v76
	v_lshlrev_b32_e32 v77, 16, v77
	v_mul_f32_e32 v74, v68, v74
	v_mul_f32_e32 v75, v68, v75
	v_mul_f32_e32 v76, v68, v76
	v_mul_f32_e32 v77, v68, v77
	v_mul_f32_e32 v4, v4, v74
	v_mul_f32_e32 v20, v20, v75
	v_mul_f32_e32 v36, v36, v76
	v_mul_f32_e32 v52, v52, v77
	s_nop 0
	v_mov_b32_dpp v70, v4 quad_perm:[1,0,3,2] row_mask:0xf bank_mask:0xf
	v_mov_b32_dpp v71, v20 quad_perm:[1,0,3,2] row_mask:0xf bank_mask:0xf
	v_mov_b32_dpp v72, v36 quad_perm:[1,0,3,2] row_mask:0xf bank_mask:0xf
	v_mov_b32_dpp v73, v52 quad_perm:[1,0,3,2] row_mask:0xf bank_mask:0xf
	v_cvt_pk_bf16_f32 v4, v4, v70
	v_cvt_pk_bf16_f32 v20, v20, v71
	v_cvt_pk_bf16_f32 v36, v36, v72
	v_cvt_pk_bf16_f32 v52, v52, v73
	ds_read_u16 v74, v78 offset:17152
	ds_read_u16 v75, v78 offset:17216
	ds_read_u16 v76, v78 offset:17280
	ds_read_u16 v77, v78 offset:17344
	s_waitcnt lgkmcnt(0)
; __device__ __forceinline__ float bf2f(unsigned h) { return __uint_as_float(h << 16); }
; __device__ __forceinline__ unsigned cvt_pk_bf16(float lo, float hi) { unsigned r; asm volatile("v_cvt_pk_bf16_f32 %0, %1, %2" : "=v"(r) : "v"(lo), "v"(hi)); return r; }
; __device__ __forceinline__ int crow(int r, int hi) { return (r & 3) + 8 * (r >> 2) + 4 * hi; }
; __device__ __forceinline__ void retout_phase(const bf16_t* RQ, const bf16_t* RK, const bf16_t* RV, const bf16_t* RG, const bf16_t* ST, bf16_t* Y, lptr lds, int blk, int G, int tid_) {
;     ...
;         for (int r = 0; r < 16; ++r) { const int tr = crow(r, hi);
;             float v0 = o[0][r], v1 = o[1][r], v2 = o[2][r], v3 = o[3][r];
;             float ss = (v0 * v0 + v1 * v1) + (v2 * v2 + v3 * v3);
;             ss += __shfl_xor(ss, 1); ss += __shfl_xor(ss, 2); ss += __shfl_xor(ss, 4); ss += __shfl_xor(ss, 8); ss += __shfl_xor(ss, 16);
;             const float rs = rsqrtf(ss * (1.0f / 128.0f) + EPS);
;             v0 *= rs * bf2f(gp[tr * HD]); v1 *= rs * bf2f(gp[tr * HD + 32]); v2 *= rs * bf2f(gp[tr * HD + 64]); v3 *= rs * bf2f(gp[tr * HD + 96]);
;             const float n0 = __shfl_xor(v0, 1), n1 = __shfl_xor(v1, 1), n2 = __shfl_xor(v2, 1), n3 = __shfl_xor(v3, 1);
;             if ((r32 & 1) == 0) { bf16_t* op = yp + (size_t)tr * DM;
;                 *(unsigned*)(op) = cvt_pk_bf16(v0, n0); *(unsigned*)(op + 32) = cvt_pk_bf16(v1, n1); *(unsigned*)(op + 64) = cvt_pk_bf16(v2, n2); *(unsigned*)(op + 96) = cvt_pk_bf16(v3, n3); } }
	v_lshlrev_b32_e32 v74, 16, v74
	v_lshlrev_b32_e32 v75, 16, v75
	v_lshlrev_b32_e32 v76, 16, v76
	v_lshlrev_b32_e32 v77, 16, v77
	v_mul_f32_e32 v74, v69, v74
	v_mul_f32_e32 v75, v69, v75
	v_mul_f32_e32 v76, v69, v76
	v_mul_f32_e32 v77, v69, v77
	v_mul_f32_e32 v5, v5, v74
	v_mul_f32_e32 v21, v21, v75
	v_mul_f32_e32 v37, v37, v76
	v_mul_f32_e32 v53, v53, v77
	s_nop 0
	v_mov_b32_dpp v70, v5 quad_perm:[1,0,3,2] row_mask:0xf bank_mask:0xf
	v_mov_b32_dpp v71, v21 quad_perm:[1,0,3,2] row_mask:0xf bank_mask:0xf
	v_mov_b32_dpp v72, v37 quad_perm:[1,0,3,2] row_mask:0xf bank_mask:0xf
	v_mov_b32_dpp v73, v53 quad_perm:[1,0,3,2] row_mask:0xf bank_mask:0xf
	v_cvt_pk_bf16_f32 v5, v5, v70
	v_cvt_pk_bf16_f32 v21, v21, v71
	v_cvt_pk_bf16_f32 v37, v37, v72
	v_cvt_pk_bf16_f32 v53, v53, v73
	v_pk_mul_f32 v[66:67], v[6:7], v[6:7]
	v_pk_mul_f32 v[68:69], v[8:9], v[8:9]
	v_pk_fma_f32 v[66:67], v[22:23], v[22:23], v[66:67]
	v_pk_fma_f32 v[68:69], v[24:25], v[24:25], v[68:69]
	v_pk_fma_f32 v[66:67], v[38:39], v[38:39], v[66:67]
	v_pk_fma_f32 v[68:69], v[40:41], v[40:41], v[68:69]
	v_pk_fma_f32 v[66:67], v[54:55], v[54:55], v[66:67]
	v_pk_fma_f32 v[68:69], v[56:57], v[56:57], v[68:69]
	s_nop 1
	v_add_f32_dpp v66, v66, v66 quad_perm:[1,0,3,2] row_mask:0xf bank_mask:0xf
	v_add_f32_dpp v67, v67, v67 quad_perm:[1,0,3,2] row_mask:0xf bank_mask:0xf
	v_add_f32_dpp v68, v68, v68 quad_perm:[1,0,3,2] row_mask:0xf bank_mask:0xf
	v_add_f32_dpp v69, v69, v69 quad_perm:[1,0,3,2] row_mask:0xf bank_mask:0xf
	v_add_f32_dpp v66, v66, v66 quad_perm:[2,3,0,1] row_mask:0xf bank_mask:0xf
	v_add_f32_dpp v67, v67, v67 quad_perm:[2,3,0,1] row_mask:0xf bank_mask:0xf
	v_add_f32_dpp v68, v68, v68 quad_perm:[2,3,0,1] row_mask:0xf bank_mask:0xf
	v_add_f32_dpp v69, v69, v69 quad_perm:[2,3,0,1] row_mask:0xf bank_mask:0xf
	v_add_f32_dpp v66, v66, v66 row_half_mirror row_mask:0xf bank_mask:0xf
	v_add_f32_dpp v67, v67, v67 row_half_mirror row_mask:0xf bank_mask:0xf
	v_add_f32_dpp v68, v68, v68 row_half_mirror row_mask:0xf bank_mask:0xf
	v_add_f32_dpp v69, v69, v69 row_half_mirror row_mask:0xf bank_mask:0xf
	v_add_f32_dpp v66, v66, v66 row_mirror row_mask:0xf bank_mask:0xf
	v_add_f32_dpp v67, v67, v67 row_mirror row_mask:0xf bank_mask:0xf
	v_add_f32_dpp v68, v68, v68 row_mirror row_mask:0xf bank_mask:0xf
	v_add_f32_dpp v69, v69, v69 row_mirror row_mask:0xf bank_mask:0xf
	v_mov_b32_e32 v70, v66
	v_mov_b32_e32 v71, v67
	v_mov_b32_e32 v72, v68
	v_mov_b32_e32 v73, v69
	v_permlane16_swap_b32_e32 v66, v70
	v_permlane16_swap_b32_e32 v67, v71
	v_permlane16_swap_b32_e32 v68, v72
	v_permlane16_swap_b32_e32 v69, v73
	v_add_f32_e32 v66, v66, v70
	v_add_f32_e32 v67, v67, v71
	v_add_f32_e32 v68, v68, v72
	v_add_f32_e32 v69, v69, v73
	v_fmamk_f32 v66, v66, 0x3c000000, v192
	v_fmamk_f32 v67, v67, 0x3c000000, v192
	v_fmamk_f32 v68, v68, 0x3c000000, v192
	v_fmamk_f32 v69, v69, 0x3c000000, v192
	v_rsq_f32_e32 v66, v66
	v_rsq_f32_e32 v67, v67
	v_rsq_f32_e32 v68, v68
	v_rsq_f32_e32 v69, v69
	ds_read_u16 v74, v78 offset:18432
	ds_read_u16 v75, v78 offset:18496
	ds_read_u16 v76, v78 offset:18560
	ds_read_u16 v77, v78 offset:18624
	s_waitcnt lgkmcnt(0)
	v_lshlrev_b32_e32 v74, 16, v74
	v_lshlrev_b32_e32 v75, 16, v75
	v_lshlrev_b32_e32 v76, 16, v76
	v_lshlrev_b32_e32 v77, 16, v77
	v_mul_f32_e32 v74, v66, v74
	v_mul_f32_e32 v75, v66, v75
	v_mul_f32_e32 v76, v66, v76
	v_mul_f32_e32 v77, v66, v77
	v_mul_f32_e32 v6, v6, v74
	v_mul_f32_e32 v22, v22, v75
	v_mul_f32_e32 v38, v38, v76
	v_mul_f32_e32 v54, v54, v77
	s_nop 0
	v_mov_b32_dpp v70, v6 quad_perm:[1,0,3,2] row_mask:0xf bank_mask:0xf
	v_mov_b32_dpp v71, v22 quad_perm:[1,0,3,2] row_mask:0xf bank_mask:0xf
	v_mov_b32_dpp v72, v38 quad_perm:[1,0,3,2] row_mask:0xf bank_mask:0xf
	v_mov_b32_dpp v73, v54 quad_perm:[1,0,3,2] row_mask:0xf bank_mask:0xf
	v_cvt_pk_bf16_f32 v6, v6, v70
	v_cvt_pk_bf16_f32 v22, v22, v71
	v_cvt_pk_bf16_f32 v38, v38, v72
	v_cvt_pk_bf16_f32 v54, v54, v73
	ds_read_u16 v74, v78 offset:18688
	ds_read_u16 v75, v78 offset:18752
	ds_read_u16 v76, v78 offset:18816
	ds_read_u16 v77, v78 offset:18880
	s_waitcnt lgkmcnt(0)
	v_lshlrev_b32_e32 v74, 16, v74
	v_lshlrev_b32_e32 v75, 16, v75
	v_lshlrev_b32_e32 v76, 16, v76
	v_lshlrev_b32_e32 v77, 16, v77
	v_mul_f32_e32 v74, v67, v74
	v_mul_f32_e32 v75, v67, v75
	v_mul_f32_e32 v76, v67, v76
	v_mul_f32_e32 v77, v67, v77
	v_mul_f32_e32 v7, v7, v74
	v_mul_f32_e32 v23, v23, v75
	v_mul_f32_e32 v39, v39, v76
	v_mul_f32_e32 v55, v55, v77
	s_nop 0
	v_mov_b32_dpp v70, v7 quad_perm:[1,0,3,2] row_mask:0xf bank_mask:0xf
	v_mov_b32_dpp v71, v23 quad_perm:[1,0,3,2] row_mask:0xf bank_mask:0xf
	v_mov_b32_dpp v72, v39 quad_perm:[1,0,3,2] row_mask:0xf bank_mask:0xf
	v_mov_b32_dpp v73, v55 quad_perm:[1,0,3,2] row_mask:0xf bank_mask:0xf
	v_cvt_pk_bf16_f32 v7, v7, v70
	v_cvt_pk_bf16_f32 v23, v23, v71
	v_cvt_pk_bf16_f32 v39, v39, v72
	v_cvt_pk_bf16_f32 v55, v55, v73
	ds_read_u16 v74, v78 offset:18944
	ds_read_u16 v75, v78 offset:19008
	ds_read_u16 v76, v78 offset:19072
	ds_read_u16 v77, v78 offset:19136
	s_waitcnt lgkmcnt(0)
	v_lshlrev_b32_e32 v74, 16, v74
	v_lshlrev_b32_e32 v75, 16, v75
	v_lshlrev_b32_e32 v76, 16, v76
	v_lshlrev_b32_e32 v77, 16, v77
	v_mul_f32_e32 v74, v68, v74
	v_mul_f32_e32 v75, v68, v75
	v_mul_f32_e32 v76, v68, v76
	v_mul_f32_e32 v77, v68, v77
	v_mul_f32_e32 v8, v8, v74
	v_mul_f32_e32 v24, v24, v75
	v_mul_f32_e32 v40, v40, v76
	v_mul_f32_e32 v56, v56, v77
	s_nop 0
	v_mov_b32_dpp v70, v8 quad_perm:[1,0,3,2] row_mask:0xf bank_mask:0xf
	v_mov_b32_dpp v71, v24 quad_perm:[1,0,3,2] row_mask:0xf bank_mask:0xf
	v_mov_b32_dpp v72, v40 quad_perm:[1,0,3,2] row_mask:0xf bank_mask:0xf
	v_mov_b32_dpp v73, v56 quad_perm:[1,0,3,2] row_mask:0xf bank_mask:0xf
	v_cvt_pk_bf16_f32 v8, v8, v70
	v_cvt_pk_bf16_f32 v24, v24, v71
	v_cvt_pk_bf16_f32 v40, v40, v72
	v_cvt_pk_bf16_f32 v56, v56, v73
	ds_read_u16 v74, v78 offset:19200
	ds_read_u16 v75, v78 offset:19264
	ds_read_u16 v76, v78 offset:19328
	ds_read_u16 v77, v78 offset:19392
	s_waitcnt lgkmcnt(0)
; __device__ __forceinline__ float bf2f(unsigned h) { return __uint_as_float(h << 16); }
; __device__ __forceinline__ unsigned cvt_pk_bf16(float lo, float hi) { unsigned r; asm volatile("v_cvt_pk_bf16_f32 %0, %1, %2" : "=v"(r) : "v"(lo), "v"(hi)); return r; }
; __device__ __forceinline__ int crow(int r, int hi) { return (r & 3) + 8 * (r >> 2) + 4 * hi; }
; __device__ __forceinline__ void retout_phase(const bf16_t* RQ, const bf16_t* RK, const bf16_t* RV, const bf16_t* RG, const bf16_t* ST, bf16_t* Y, lptr lds, int blk, int G, int tid_) {
;     ...
;         for (int r = 0; r < 16; ++r) { const int tr = crow(r, hi);
;             float v0 = o[0][r], v1 = o[1][r], v2 = o[2][r], v3 = o[3][r];
;             float ss = (v0 * v0 + v1 * v1) + (v2 * v2 + v3 * v3);
;             ss += __shfl_xor(ss, 1); ss += __shfl_xor(ss, 2); ss += __shfl_xor(ss, 4); ss += __shfl_xor(ss, 8); ss += __shfl_xor(ss, 16);
;             const float rs = rsqrtf(ss * (1.0f / 128.0f) + EPS);
;             v0 *= rs * bf2f(gp[tr * HD]); v1 *= rs * bf2f(gp[tr * HD + 32]); v2 *= rs * bf2f(gp[tr * HD + 64]); v3 *= rs * bf2f(gp[tr * HD + 96]);
;             const float n0 = __shfl_xor(v0, 1), n1 = __shfl_xor(v1, 1), n2 = __shfl_xor(v2, 1), n3 = __shfl_xor(v3, 1);
;             if ((r32 & 1) == 0) { bf16_t* op = yp + (size_t)tr * DM;
;                 *(unsigned*)(op) = cvt_pk_bf16(v0, n0); *(unsigned*)(op + 32) = cvt_pk_bf16(v1, n1); *(unsigned*)(op + 64) = cvt_pk_bf16(v2, n2); *(unsigned*)(op + 96) = cvt_pk_bf16(v3, n3); } }
	v_lshlrev_b32_e32 v74, 16, v74
	v_lshlrev_b32_e32 v75, 16, v75
	v_lshlrev_b32_e32 v76, 16, v76
	v_lshlrev_b32_e32 v77, 16, v77
	v_mul_f32_e32 v74, v69, v74
	v_mul_f32_e32 v75, v69, v75
	v_mul_f32_e32 v76, v69, v76
	v_mul_f32_e32 v77, v69, v77
	v_mul_f32_e32 v9, v9, v74
	v_mul_f32_e32 v25, v25, v75
	v_mul_f32_e32 v41, v41, v76
	v_mul_f32_e32 v57, v57, v77
	s_nop 0
	v_mov_b32_dpp v70, v9 quad_perm:[1,0,3,2] row_mask:0xf bank_mask:0xf
	v_mov_b32_dpp v71, v25 quad_perm:[1,0,3,2] row_mask:0xf bank_mask:0xf
	v_mov_b32_dpp v72, v41 quad_perm:[1,0,3,2] row_mask:0xf bank_mask:0xf
	v_mov_b32_dpp v73, v57 quad_perm:[1,0,3,2] row_mask:0xf bank_mask:0xf
	v_cvt_pk_bf16_f32 v9, v9, v70
	v_cvt_pk_bf16_f32 v25, v25, v71
	v_cvt_pk_bf16_f32 v41, v41, v72
	v_cvt_pk_bf16_f32 v57, v57, v73
	v_pk_mul_f32 v[66:67], v[10:11], v[10:11]
	v_pk_mul_f32 v[68:69], v[12:13], v[12:13]
	v_pk_fma_f32 v[66:67], v[26:27], v[26:27], v[66:67]
	v_pk_fma_f32 v[68:69], v[28:29], v[28:29], v[68:69]
	v_pk_fma_f32 v[66:67], v[42:43], v[42:43], v[66:67]
	v_pk_fma_f32 v[68:69], v[44:45], v[44:45], v[68:69]
	v_pk_fma_f32 v[66:67], v[58:59], v[58:59], v[66:67]
	v_pk_fma_f32 v[68:69], v[60:61], v[60:61], v[68:69]
	s_nop 1
	v_add_f32_dpp v66, v66, v66 quad_perm:[1,0,3,2] row_mask:0xf bank_mask:0xf
	v_add_f32_dpp v67, v67, v67 quad_perm:[1,0,3,2] row_mask:0xf bank_mask:0xf
	v_add_f32_dpp v68, v68, v68 quad_perm:[1,0,3,2] row_mask:0xf bank_mask:0xf
	v_add_f32_dpp v69, v69, v69 quad_perm:[1,0,3,2] row_mask:0xf bank_mask:0xf
	v_add_f32_dpp v66, v66, v66 quad_perm:[2,3,0,1] row_mask:0xf bank_mask:0xf
	v_add_f32_dpp v67, v67, v67 quad_perm:[2,3,0,1] row_mask:0xf bank_mask:0xf
	v_add_f32_dpp v68, v68, v68 quad_perm:[2,3,0,1] row_mask:0xf bank_mask:0xf
	v_add_f32_dpp v69, v69, v69 quad_perm:[2,3,0,1] row_mask:0xf bank_mask:0xf
	v_add_f32_dpp v66, v66, v66 row_half_mirror row_mask:0xf bank_mask:0xf
	v_add_f32_dpp v67, v67, v67 row_half_mirror row_mask:0xf bank_mask:0xf
	v_add_f32_dpp v68, v68, v68 row_half_mirror row_mask:0xf bank_mask:0xf
	v_add_f32_dpp v69, v69, v69 row_half_mirror row_mask:0xf bank_mask:0xf
	v_add_f32_dpp v66, v66, v66 row_mirror row_mask:0xf bank_mask:0xf
	v_add_f32_dpp v67, v67, v67 row_mirror row_mask:0xf bank_mask:0xf
	v_add_f32_dpp v68, v68, v68 row_mirror row_mask:0xf bank_mask:0xf
	v_add_f32_dpp v69, v69, v69 row_mirror row_mask:0xf bank_mask:0xf
	v_mov_b32_e32 v70, v66
	v_mov_b32_e32 v71, v67
	v_mov_b32_e32 v72, v68
	v_mov_b32_e32 v73, v69
	v_permlane16_swap_b32_e32 v66, v70
	v_permlane16_swap_b32_e32 v67, v71
	v_permlane16_swap_b32_e32 v68, v72
	v_permlane16_swap_b32_e32 v69, v73
	v_add_f32_e32 v66, v66, v70
	v_add_f32_e32 v67, v67, v71
	v_add_f32_e32 v68, v68, v72
	v_add_f32_e32 v69, v69, v73
	v_fmamk_f32 v66, v66, 0x3c000000, v192
	v_fmamk_f32 v67, v67, 0x3c000000, v192
	v_fmamk_f32 v68, v68, 0x3c000000, v192
	v_fmamk_f32 v69, v69, 0x3c000000, v192
	v_rsq_f32_e32 v66, v66
	v_rsq_f32_e32 v67, v67
	v_rsq_f32_e32 v68, v68
	v_rsq_f32_e32 v69, v69
	ds_read_u16 v74, v78 offset:20480
	ds_read_u16 v75, v78 offset:20544
	ds_read_u16 v76, v78 offset:20608
	ds_read_u16 v77, v78 offset:20672
	s_waitcnt lgkmcnt(0)
	v_lshlrev_b32_e32 v74, 16, v74
	v_lshlrev_b32_e32 v75, 16, v75
	v_lshlrev_b32_e32 v76, 16, v76
	v_lshlrev_b32_e32 v77, 16, v77
	v_mul_f32_e32 v74, v66, v74
	v_mul_f32_e32 v75, v66, v75
	v_mul_f32_e32 v76, v66, v76
	v_mul_f32_e32 v77, v66, v77
	v_mul_f32_e32 v10, v10, v74
	v_mul_f32_e32 v26, v26, v75
	v_mul_f32_e32 v42, v42, v76
	v_mul_f32_e32 v58, v58, v77
	s_nop 0
	v_mov_b32_dpp v70, v10 quad_perm:[1,0,3,2] row_mask:0xf bank_mask:0xf
	v_mov_b32_dpp v71, v26 quad_perm:[1,0,3,2] row_mask:0xf bank_mask:0xf
	v_mov_b32_dpp v72, v42 quad_perm:[1,0,3,2] row_mask:0xf bank_mask:0xf
	v_mov_b32_dpp v73, v58 quad_perm:[1,0,3,2] row_mask:0xf bank_mask:0xf
	v_cvt_pk_bf16_f32 v10, v10, v70
	v_cvt_pk_bf16_f32 v26, v26, v71
	v_cvt_pk_bf16_f32 v42, v42, v72
	v_cvt_pk_bf16_f32 v58, v58, v73
	ds_read_u16 v74, v78 offset:20736
	ds_read_u16 v75, v78 offset:20800
	ds_read_u16 v76, v78 offset:20864
	ds_read_u16 v77, v78 offset:20928
	s_waitcnt lgkmcnt(0)
	v_lshlrev_b32_e32 v74, 16, v74
	v_lshlrev_b32_e32 v75, 16, v75
	v_lshlrev_b32_e32 v76, 16, v76
	v_lshlrev_b32_e32 v77, 16, v77
	v_mul_f32_e32 v74, v67, v74
	v_mul_f32_e32 v75, v67, v75
	v_mul_f32_e32 v76, v67, v76
	v_mul_f32_e32 v77, v67, v77
	v_mul_f32_e32 v11, v11, v74
	v_mul_f32_e32 v27, v27, v75
	v_mul_f32_e32 v43, v43, v76
	v_mul_f32_e32 v59, v59, v77
	s_nop 0
	v_mov_b32_dpp v70, v11 quad_perm:[1,0,3,2] row_mask:0xf bank_mask:0xf
	v_mov_b32_dpp v71, v27 quad_perm:[1,0,3,2] row_mask:0xf bank_mask:0xf
	v_mov_b32_dpp v72, v43 quad_perm:[1,0,3,2] row_mask:0xf bank_mask:0xf
	v_mov_b32_dpp v73, v59 quad_perm:[1,0,3,2] row_mask:0xf bank_mask:0xf
	v_cvt_pk_bf16_f32 v11, v11, v70
	v_cvt_pk_bf16_f32 v27, v27, v71
	v_cvt_pk_bf16_f32 v43, v43, v72
	v_cvt_pk_bf16_f32 v59, v59, v73
	ds_read_u16 v74, v78 offset:20992
	ds_read_u16 v75, v78 offset:21056
	ds_read_u16 v76, v78 offset:21120
	ds_read_u16 v77, v78 offset:21184
	s_waitcnt lgkmcnt(0)
	v_lshlrev_b32_e32 v74, 16, v74
	v_lshlrev_b32_e32 v75, 16, v75
	v_lshlrev_b32_e32 v76, 16, v76
	v_lshlrev_b32_e32 v77, 16, v77
	v_mul_f32_e32 v74, v68, v74
	v_mul_f32_e32 v75, v68, v75
	v_mul_f32_e32 v76, v68, v76
	v_mul_f32_e32 v77, v68, v77
	v_mul_f32_e32 v12, v12, v74
	v_mul_f32_e32 v28, v28, v75
	v_mul_f32_e32 v44, v44, v76
	v_mul_f32_e32 v60, v60, v77
	s_nop 0
	v_mov_b32_dpp v70, v12 quad_perm:[1,0,3,2] row_mask:0xf bank_mask:0xf
	v_mov_b32_dpp v71, v28 quad_perm:[1,0,3,2] row_mask:0xf bank_mask:0xf
	v_mov_b32_dpp v72, v44 quad_perm:[1,0,3,2] row_mask:0xf bank_mask:0xf
	v_mov_b32_dpp v73, v60 quad_perm:[1,0,3,2] row_mask:0xf bank_mask:0xf
	v_cvt_pk_bf16_f32 v12, v12, v70
	v_cvt_pk_bf16_f32 v28, v28, v71
	v_cvt_pk_bf16_f32 v44, v44, v72
	v_cvt_pk_bf16_f32 v60, v60, v73
	ds_read_u16 v74, v78 offset:21248
	ds_read_u16 v75, v78 offset:21312
	ds_read_u16 v76, v78 offset:21376
	ds_read_u16 v77, v78 offset:21440
	s_waitcnt lgkmcnt(0)
; __device__ __forceinline__ float bf2f(unsigned h) { return __uint_as_float(h << 16); }
; __device__ __forceinline__ unsigned cvt_pk_bf16(float lo, float hi) { unsigned r; asm volatile("v_cvt_pk_bf16_f32 %0, %1, %2" : "=v"(r) : "v"(lo), "v"(hi)); return r; }
; __device__ __forceinline__ int crow(int r, int hi) { return (r & 3) + 8 * (r >> 2) + 4 * hi; }
; __device__ __forceinline__ void retout_phase(const bf16_t* RQ, const bf16_t* RK, const bf16_t* RV, const bf16_t* RG, const bf16_t* ST, bf16_t* Y, lptr lds, int blk, int G, int tid_) {
;     ...
;         for (int r = 0; r < 16; ++r) { const int tr = crow(r, hi);
;             float v0 = o[0][r], v1 = o[1][r], v2 = o[2][r], v3 = o[3][r];
;             float ss = (v0 * v0 + v1 * v1) + (v2 * v2 + v3 * v3);
;             ss += __shfl_xor(ss, 1); ss += __shfl_xor(ss, 2); ss += __shfl_xor(ss, 4); ss += __shfl_xor(ss, 8); ss += __shfl_xor(ss, 16);
;             const float rs = rsqrtf(ss * (1.0f / 128.0f) + EPS);
;             v0 *= rs * bf2f(gp[tr * HD]); v1 *= rs * bf2f(gp[tr * HD + 32]); v2 *= rs * bf2f(gp[tr * HD + 64]); v3 *= rs * bf2f(gp[tr * HD + 96]);
;             const float n0 = __shfl_xor(v0, 1), n1 = __shfl_xor(v1, 1), n2 = __shfl_xor(v2, 1), n3 = __shfl_xor(v3, 1);
;             if ((r32 & 1) == 0) { bf16_t* op = yp + (size_t)tr * DM;
;                 *(unsigned*)(op) = cvt_pk_bf16(v0, n0); *(unsigned*)(op + 32) = cvt_pk_bf16(v1, n1); *(unsigned*)(op + 64) = cvt_pk_bf16(v2, n2); *(unsigned*)(op + 96) = cvt_pk_bf16(v3, n3); } }
	v_lshlrev_b32_e32 v74, 16, v74
	v_lshlrev_b32_e32 v75, 16, v75
	v_lshlrev_b32_e32 v76, 16, v76
	v_lshlrev_b32_e32 v77, 16, v77
	v_mul_f32_e32 v74, v69, v74
	v_mul_f32_e32 v75, v69, v75
	v_mul_f32_e32 v76, v69, v76
	v_mul_f32_e32 v77, v69, v77
	v_mul_f32_e32 v13, v13, v74
	v_mul_f32_e32 v29, v29, v75
	v_mul_f32_e32 v45, v45, v76
	v_mul_f32_e32 v61, v61, v77
	s_nop 0
	v_mov_b32_dpp v70, v13 quad_perm:[1,0,3,2] row_mask:0xf bank_mask:0xf
	v_mov_b32_dpp v71, v29 quad_perm:[1,0,3,2] row_mask:0xf bank_mask:0xf
	v_mov_b32_dpp v72, v45 quad_perm:[1,0,3,2] row_mask:0xf bank_mask:0xf
	v_mov_b32_dpp v73, v61 quad_perm:[1,0,3,2] row_mask:0xf bank_mask:0xf
	v_cvt_pk_bf16_f32 v13, v13, v70
	v_cvt_pk_bf16_f32 v29, v29, v71
	v_cvt_pk_bf16_f32 v45, v45, v72
	v_cvt_pk_bf16_f32 v61, v61, v73
	v_pk_mul_f32 v[66:67], v[14:15], v[14:15]
	v_pk_mul_f32 v[68:69], v[16:17], v[16:17]
	v_pk_fma_f32 v[66:67], v[30:31], v[30:31], v[66:67]
	v_pk_fma_f32 v[68:69], v[32:33], v[32:33], v[68:69]
	v_pk_fma_f32 v[66:67], v[46:47], v[46:47], v[66:67]
	v_pk_fma_f32 v[68:69], v[48:49], v[48:49], v[68:69]
	v_pk_fma_f32 v[66:67], v[62:63], v[62:63], v[66:67]
	v_pk_fma_f32 v[68:69], v[64:65], v[64:65], v[68:69]
	s_nop 1
	v_add_f32_dpp v66, v66, v66 quad_perm:[1,0,3,2] row_mask:0xf bank_mask:0xf
	v_add_f32_dpp v67, v67, v67 quad_perm:[1,0,3,2] row_mask:0xf bank_mask:0xf
	v_add_f32_dpp v68, v68, v68 quad_perm:[1,0,3,2] row_mask:0xf bank_mask:0xf
	v_add_f32_dpp v69, v69, v69 quad_perm:[1,0,3,2] row_mask:0xf bank_mask:0xf
	v_add_f32_dpp v66, v66, v66 quad_perm:[2,3,0,1] row_mask:0xf bank_mask:0xf
	v_add_f32_dpp v67, v67, v67 quad_perm:[2,3,0,1] row_mask:0xf bank_mask:0xf
	v_add_f32_dpp v68, v68, v68 quad_perm:[2,3,0,1] row_mask:0xf bank_mask:0xf
	v_add_f32_dpp v69, v69, v69 quad_perm:[2,3,0,1] row_mask:0xf bank_mask:0xf
	v_add_f32_dpp v66, v66, v66 row_half_mirror row_mask:0xf bank_mask:0xf
	v_add_f32_dpp v67, v67, v67 row_half_mirror row_mask:0xf bank_mask:0xf
	v_add_f32_dpp v68, v68, v68 row_half_mirror row_mask:0xf bank_mask:0xf
	v_add_f32_dpp v69, v69, v69 row_half_mirror row_mask:0xf bank_mask:0xf
	v_add_f32_dpp v66, v66, v66 row_mirror row_mask:0xf bank_mask:0xf
	v_add_f32_dpp v67, v67, v67 row_mirror row_mask:0xf bank_mask:0xf
	v_add_f32_dpp v68, v68, v68 row_mirror row_mask:0xf bank_mask:0xf
	v_add_f32_dpp v69, v69, v69 row_mirror row_mask:0xf bank_mask:0xf
	v_mov_b32_e32 v70, v66
	v_mov_b32_e32 v71, v67
	v_mov_b32_e32 v72, v68
	v_mov_b32_e32 v73, v69
	v_permlane16_swap_b32_e32 v66, v70
	v_permlane16_swap_b32_e32 v67, v71
	v_permlane16_swap_b32_e32 v68, v72
	v_permlane16_swap_b32_e32 v69, v73
	v_add_f32_e32 v66, v66, v70
	v_add_f32_e32 v67, v67, v71
	v_add_f32_e32 v68, v68, v72
	v_add_f32_e32 v69, v69, v73
	v_fmamk_f32 v66, v66, 0x3c000000, v192
	v_fmamk_f32 v67, v67, 0x3c000000, v192
	v_fmamk_f32 v68, v68, 0x3c000000, v192
	v_fmamk_f32 v69, v69, 0x3c000000, v192
	v_rsq_f32_e32 v66, v66
	v_rsq_f32_e32 v67, v67
	v_rsq_f32_e32 v68, v68
	v_rsq_f32_e32 v69, v69
	ds_read_u16 v74, v78 offset:22528
	ds_read_u16 v75, v78 offset:22592
	ds_read_u16 v76, v78 offset:22656
	ds_read_u16 v77, v78 offset:22720
	s_waitcnt lgkmcnt(0)
	v_lshlrev_b32_e32 v74, 16, v74
	v_lshlrev_b32_e32 v75, 16, v75
	v_lshlrev_b32_e32 v76, 16, v76
	v_lshlrev_b32_e32 v77, 16, v77
	v_mul_f32_e32 v74, v66, v74
	v_mul_f32_e32 v75, v66, v75
	v_mul_f32_e32 v76, v66, v76
	v_mul_f32_e32 v77, v66, v77
	v_mul_f32_e32 v14, v14, v74
	v_mul_f32_e32 v30, v30, v75
	v_mul_f32_e32 v46, v46, v76
	v_mul_f32_e32 v62, v62, v77
	s_nop 0
	v_mov_b32_dpp v70, v14 quad_perm:[1,0,3,2] row_mask:0xf bank_mask:0xf
	v_mov_b32_dpp v71, v30 quad_perm:[1,0,3,2] row_mask:0xf bank_mask:0xf
	v_mov_b32_dpp v72, v46 quad_perm:[1,0,3,2] row_mask:0xf bank_mask:0xf
	v_mov_b32_dpp v73, v62 quad_perm:[1,0,3,2] row_mask:0xf bank_mask:0xf
	v_cvt_pk_bf16_f32 v14, v14, v70
	v_cvt_pk_bf16_f32 v30, v30, v71
	v_cvt_pk_bf16_f32 v46, v46, v72
	v_cvt_pk_bf16_f32 v62, v62, v73
	ds_read_u16 v74, v78 offset:22784
	ds_read_u16 v75, v78 offset:22848
	ds_read_u16 v76, v78 offset:22912
	ds_read_u16 v77, v78 offset:22976
	s_waitcnt lgkmcnt(0)
	v_lshlrev_b32_e32 v74, 16, v74
	v_lshlrev_b32_e32 v75, 16, v75
	v_lshlrev_b32_e32 v76, 16, v76
	v_lshlrev_b32_e32 v77, 16, v77
	v_mul_f32_e32 v74, v67, v74
	v_mul_f32_e32 v75, v67, v75
	v_mul_f32_e32 v76, v67, v76
	v_mul_f32_e32 v77, v67, v77
	v_mul_f32_e32 v15, v15, v74
	v_mul_f32_e32 v31, v31, v75
	v_mul_f32_e32 v47, v47, v76
	v_mul_f32_e32 v63, v63, v77
	s_nop 0
	v_mov_b32_dpp v70, v15 quad_perm:[1,0,3,2] row_mask:0xf bank_mask:0xf
	v_mov_b32_dpp v71, v31 quad_perm:[1,0,3,2] row_mask:0xf bank_mask:0xf
	v_mov_b32_dpp v72, v47 quad_perm:[1,0,3,2] row_mask:0xf bank_mask:0xf
	v_mov_b32_dpp v73, v63 quad_perm:[1,0,3,2] row_mask:0xf bank_mask:0xf
	v_cvt_pk_bf16_f32 v15, v15, v70
	v_cvt_pk_bf16_f32 v31, v31, v71
	v_cvt_pk_bf16_f32 v47, v47, v72
	v_cvt_pk_bf16_f32 v63, v63, v73
	ds_read_u16 v74, v78 offset:23040
	ds_read_u16 v75, v78 offset:23104
	ds_read_u16 v76, v78 offset:23168
	ds_read_u16 v77, v78 offset:23232
	s_waitcnt lgkmcnt(0)
; __device__ __forceinline__ float bf2f(unsigned h) { return __uint_as_float(h << 16); }
; __device__ __forceinline__ unsigned cvt_pk_bf16(float lo, float hi) { unsigned r; asm volatile("v_cvt_pk_bf16_f32 %0, %1, %2" : "=v"(r) : "v"(lo), "v"(hi)); return r; }
; __device__ __forceinline__ int crow(int r, int hi) { return (r & 3) + 8 * (r >> 2) + 4 * hi; }
; __device__ __forceinline__ void retout_phase(const bf16_t* RQ, const bf16_t* RK, const bf16_t* RV, const bf16_t* RG, const bf16_t* ST, bf16_t* Y, lptr lds, int blk, int G, int tid_) {
;     ...
;         for (int r = 0; r < 16; ++r) { const int tr = crow(r, hi);
;             float v0 = o[0][r], v1 = o[1][r], v2 = o[2][r], v3 = o[3][r];
;             float ss = (v0 * v0 + v1 * v1) + (v2 * v2 + v3 * v3);
;             ss += __shfl_xor(ss, 1); ss += __shfl_xor(ss, 2); ss += __shfl_xor(ss, 4); ss += __shfl_xor(ss, 8); ss += __shfl_xor(ss, 16);
;             const float rs = rsqrtf(ss * (1.0f / 128.0f) + EPS);
;             v0 *= rs * bf2f(gp[tr * HD]); v1 *= rs * bf2f(gp[tr * HD + 32]); v2 *= rs * bf2f(gp[tr * HD + 64]); v3 *= rs * bf2f(gp[tr * HD + 96]);
;             const float n0 = __shfl_xor(v0, 1), n1 = __shfl_xor(v1, 1), n2 = __shfl_xor(v2, 1), n3 = __shfl_xor(v3, 1);
;             if ((r32 & 1) == 0) { bf16_t* op = yp + (size_t)tr * DM;
;                 *(unsigned*)(op) = cvt_pk_bf16(v0, n0); *(unsigned*)(op + 32) = cvt_pk_bf16(v1, n1); *(unsigned*)(op + 64) = cvt_pk_bf16(v2, n2); *(unsigned*)(op + 96) = cvt_pk_bf16(v3, n3); } }
	v_lshlrev_b32_e32 v74, 16, v74
	v_lshlrev_b32_e32 v75, 16, v75
	v_lshlrev_b32_e32 v76, 16, v76
	v_lshlrev_b32_e32 v77, 16, v77
	v_mul_f32_e32 v74, v68, v74
	v_mul_f32_e32 v75, v68, v75
	v_mul_f32_e32 v76, v68, v76
	v_mul_f32_e32 v77, v68, v77
	v_mul_f32_e32 v16, v16, v74
	v_mul_f32_e32 v32, v32, v75
	v_mul_f32_e32 v48, v48, v76
	v_mul_f32_e32 v64, v64, v77
	s_nop 0
	v_mov_b32_dpp v70, v16 quad_perm:[1,0,3,2] row_mask:0xf bank_mask:0xf
	v_mov_b32_dpp v71, v32 quad_perm:[1,0,3,2] row_mask:0xf bank_mask:0xf
	v_mov_b32_dpp v72, v48 quad_perm:[1,0,3,2] row_mask:0xf bank_mask:0xf
	v_mov_b32_dpp v73, v64 quad_perm:[1,0,3,2] row_mask:0xf bank_mask:0xf
	v_cvt_pk_bf16_f32 v16, v16, v70
	v_cvt_pk_bf16_f32 v32, v32, v71
	v_cvt_pk_bf16_f32 v48, v48, v72
	v_cvt_pk_bf16_f32 v64, v64, v73
	ds_read_u16 v74, v78 offset:23296
	ds_read_u16 v75, v78 offset:23360
	ds_read_u16 v76, v78 offset:23424
	ds_read_u16 v77, v78 offset:23488
	s_waitcnt lgkmcnt(0)
	v_lshlrev_b32_e32 v74, 16, v74
	v_lshlrev_b32_e32 v75, 16, v75
	v_lshlrev_b32_e32 v76, 16, v76
	v_lshlrev_b32_e32 v77, 16, v77
	v_mul_f32_e32 v74, v69, v74
	v_mul_f32_e32 v75, v69, v75
	v_mul_f32_e32 v76, v69, v76
	v_mul_f32_e32 v77, v69, v77
	v_mul_f32_e32 v17, v17, v74
	v_mul_f32_e32 v33, v33, v75
	v_mul_f32_e32 v49, v49, v76
	v_mul_f32_e32 v65, v65, v77
	s_nop 0
	v_mov_b32_dpp v70, v17 quad_perm:[1,0,3,2] row_mask:0xf bank_mask:0xf
	v_mov_b32_dpp v71, v33 quad_perm:[1,0,3,2] row_mask:0xf bank_mask:0xf
	v_mov_b32_dpp v72, v49 quad_perm:[1,0,3,2] row_mask:0xf bank_mask:0xf
	v_mov_b32_dpp v73, v65 quad_perm:[1,0,3,2] row_mask:0xf bank_mask:0xf
	v_cvt_pk_bf16_f32 v17, v17, v70
	v_cvt_pk_bf16_f32 v33, v33, v71
	v_cvt_pk_bf16_f32 v49, v49, v72
	v_cvt_pk_bf16_f32 v65, v65, v73
	s_mov_b64 exec, vcc
	ds_write_b32 v78, v2 offset:16384
	ds_write_b32 v78, v18 offset:16448
	ds_write_b32 v78, v34 offset:16512
	ds_write_b32 v78, v50 offset:16576
	ds_write_b32 v78, v3 offset:16640
	ds_write_b32 v78, v19 offset:16704
	ds_write_b32 v78, v35 offset:16768
	ds_write_b32 v78, v51 offset:16832
	ds_write_b32 v78, v4 offset:16896
	ds_write_b32 v78, v20 offset:16960
	ds_write_b32 v78, v36 offset:17024
	ds_write_b32 v78, v52 offset:17088
	ds_write_b32 v78, v5 offset:17152
	ds_write_b32 v78, v21 offset:17216
	ds_write_b32 v78, v37 offset:17280
	ds_write_b32 v78, v53 offset:17344
	ds_write_b32 v78, v6 offset:18432
	ds_write_b32 v78, v22 offset:18496
	ds_write_b32 v78, v38 offset:18560
	ds_write_b32 v78, v54 offset:18624
	ds_write_b32 v78, v7 offset:18688
	ds_write_b32 v78, v23 offset:18752
	ds_write_b32 v78, v39 offset:18816
	ds_write_b32 v78, v55 offset:18880
	ds_write_b32 v78, v8 offset:18944
	ds_write_b32 v78, v24 offset:19008
	ds_write_b32 v78, v40 offset:19072
	ds_write_b32 v78, v56 offset:19136
	ds_write_b32 v78, v9 offset:19200
	ds_write_b32 v78, v25 offset:19264
	ds_write_b32 v78, v41 offset:19328
	ds_write_b32 v78, v57 offset:19392
	ds_write_b32 v78, v10 offset:20480
	ds_write_b32 v78, v26 offset:20544
	ds_write_b32 v78, v42 offset:20608
	ds_write_b32 v78, v58 offset:20672
	ds_write_b32 v78, v11 offset:20736
	ds_write_b32 v78, v27 offset:20800
	ds_write_b32 v78, v43 offset:20864
	ds_write_b32 v78, v59 offset:20928
	ds_write_b32 v78, v12 offset:20992
	ds_write_b32 v78, v28 offset:21056
	ds_write_b32 v78, v44 offset:21120
	ds_write_b32 v78, v60 offset:21184
	ds_write_b32 v78, v13 offset:21248
	ds_write_b32 v78, v29 offset:21312
	ds_write_b32 v78, v45 offset:21376
	ds_write_b32 v78, v61 offset:21440
	ds_write_b32 v78, v14 offset:22528
	ds_write_b32 v78, v30 offset:22592
	ds_write_b32 v78, v46 offset:22656
	ds_write_b32 v78, v62 offset:22720
	ds_write_b32 v78, v15 offset:22784
	ds_write_b32 v78, v31 offset:22848
	ds_write_b32 v78, v47 offset:22912
	ds_write_b32 v78, v63 offset:22976
	ds_write_b32 v78, v16 offset:23040
	ds_write_b32 v78, v32 offset:23104
	ds_write_b32 v78, v48 offset:23168
	ds_write_b32 v78, v64 offset:23232
	ds_write_b32 v78, v17 offset:23296
	ds_write_b32 v78, v33 offset:23360
	ds_write_b32 v78, v49 offset:23424
	ds_write_b32 v78, v65 offset:23488
	s_mov_b64 exec, -1
	v_lshlrev_b32_e32 v66, 4, v123
	v_lshrrev_b32_e32 v67, 4, v123
	v_and_b32_e32 v68, 15, v123
	v_lshl_add_u32 v66, v124, 9, v66
	v_lshl_add_u32 v67, v124, 1, v67
	v_lshlrev_b32_e32 v68, 4, v68
	v_add_u32_e32 v66, s27, v66
	v_lshl_add_u32 v162, v67, 12, v68
	ds_read_b128 v[4:7], v66 offset:16384
	ds_read_b128 v[8:11], v66 offset:17408
	ds_read_b128 v[12:15], v66 offset:18432
	ds_read_b128 v[16:19], v66 offset:19456
	ds_read_b128 v[20:23], v66 offset:20480
	ds_read_b128 v[24:27], v66 offset:21504
	ds_read_b128 v[28:31], v66 offset:22528
	ds_read_b128 v[32:35], v66 offset:23552
	s_waitcnt lgkmcnt(7)
	global_store_dwordx4 v162, v[4:7], s[4:5]
	s_add_u32 s4, s4, 0x4000
	s_addc_u32 s5, s5, 0
	s_waitcnt lgkmcnt(6)
	global_store_dwordx4 v162, v[8:11], s[4:5]
	s_add_u32 s4, s4, 0x4000
	s_addc_u32 s5, s5, 0
	s_waitcnt lgkmcnt(5)
	global_store_dwordx4 v162, v[12:15], s[4:5]
	s_add_u32 s4, s4, 0x4000
	s_addc_u32 s5, s5, 0
	s_waitcnt lgkmcnt(4)
	global_store_dwordx4 v162, v[16:19], s[4:5]
	s_add_u32 s4, s4, 0x4000
	s_addc_u32 s5, s5, 0
	s_waitcnt lgkmcnt(3)
	global_store_dwordx4 v162, v[20:23], s[4:5]
	s_add_u32 s4, s4, 0x4000
	s_addc_u32 s5, s5, 0
	s_waitcnt lgkmcnt(2)
	global_store_dwordx4 v162, v[24:27], s[4:5]
	s_add_u32 s4, s4, 0x4000
	s_addc_u32 s5, s5, 0
	s_waitcnt lgkmcnt(1)
	global_store_dwordx4 v162, v[28:31], s[4:5]
	s_add_u32 s4, s4, 0x4000
	s_addc_u32 s5, s5, 0
	s_waitcnt lgkmcnt(0)
	global_store_dwordx4 v162, v[32:35], s[4:5]
	s_mov_b64 exec, -1
	s_mov_b64 s[4:5], -1
	s_branch .LBB0_777

; __device__ __forceinline__ unsigned cvt_pk_bf16(float lo, float hi) { unsigned r; asm volatile("v_cvt_pk_bf16_f32 %0, %1, %2" : "=v"(r) : "v"(lo), "v"(hi)); return r; }
; __device__ __forceinline__ int crow(int r, int hi) { return (r & 3) + 8 * (r >> 2) + 4 * hi; }
; __device__ __forceinline__ void block(const BlockRef& cur, const int j0, const int NT, const int split, const SplitRef sp, lptr lds, int tid) {
;     ...
;     if (hi == 0) li_l[r32] = l_reg; asm volatile("s_waitcnt lgkmcnt(0)" ::: "memory");
;     bf16_t* Ow = cur.O + (size_t)(wid * QBLK) * DM;
; #pragma unroll
;     for (int r = 0; r < 16; ++r) { const int orow = crow(r, hi); const float rli = __builtin_amdgcn_rcpf(li_l[orow]);
;         float v0 = o[0][r] * rli, v1 = o[1][r] * rli, v2 = o[2][r] * rli, v3 = o[3][r] * rli;
;         float ss = (v0 * v0 + v1 * v1) + (v2 * v2 + v3 * v3);
;         ss += __shfl_xor(ss, 1); ss += __shfl_xor(ss, 2); ss += __shfl_xor(ss, 4); ss += __shfl_xor(ss, 8); ss += __shfl_xor(ss, 16);
;         const float rs = rsqrtf(ss * (1.0f / 128.0f) + EPS);
;         v0 *= rs; v1 *= rs; v2 *= rs; v3 *= rs;
;         const float n0 = __shfl_xor(v0, 1), n1 = __shfl_xor(v1, 1), n2 = __shfl_xor(v2, 1), n3 = __shfl_xor(v3, 1);
;         if ((r32 & 1) == 0) { bf16_t* op = Ow + (size_t)orow * DM + r32;
;             *(unsigned*)(op) = cvt_pk_bf16(v0, n0); *(unsigned*)(op + 32) = cvt_pk_bf16(v1, n1); *(unsigned*)(op + 64) = cvt_pk_bf16(v2, n2); *(unsigned*)(op + 96) = cvt_pk_bf16(v3, n3); } }
.LBB0_916:
	v_cmp_gt_u32_e32 vcc, 32, v216
	s_and_saveexec_b64 s[4:5], vcc
	v_lshl_add_u32 v1, v219, 2, s1
	ds_write_b32 v1, v220
	s_or_b64 exec, exec, s[4:5]
	s_waitcnt lgkmcnt(0)
	s_lshl_b32 s1, s96, 21
	s_and_b32 s1, s1, 0x3000000
	v_readlane_b32 s4, v255, 13
	s_add_u32 s1, s4, s1
	v_readlane_b32 s4, v255, 14
	s_addc_u32 s4, s4, 0
	s_lshl_b32 s5, s96, 8
	s_and_b32 s5, s5, 0x700
	s_add_u32 s1, s1, s5
	s_addc_u32 s6, s4, 0
	s_lshl_b64 s[4:5], s[74:75], 20
	s_add_u32 s4, s1, s4
	s_addc_u32 s5, s6, s5
	s_ashr_i32 s1, s0, 31
	s_lshl_b64 s[0:1], s[0:1], 12
	s_add_u32 s4, s4, s0
	s_addc_u32 s5, s5, s1
	v_and_b32_e32 v1, 1, v174
	v_cmp_eq_u32_e32 vcc, 0, v1
	ds_read_b32 v66, v218
	ds_read_b32 v67, v218 offset:4
	ds_read_b32 v68, v218 offset:8
	ds_read_b32 v69, v218 offset:12
	s_waitcnt lgkmcnt(0)
	v_rcp_f32_e32 v66, v66
	v_rcp_f32_e32 v67, v67
	v_rcp_f32_e32 v68, v68
	v_rcp_f32_e32 v69, v69
	v_pk_mul_f32 v[50:51], v[50:51], v[66:67]
	v_pk_mul_f32 v[34:35], v[34:35], v[66:67]
	v_pk_mul_f32 v[18:19], v[18:19], v[66:67]
	v_pk_mul_f32 v[2:3], v[2:3], v[66:67]
	v_pk_mul_f32 v[52:53], v[52:53], v[68:69]
	v_pk_mul_f32 v[36:37], v[36:37], v[68:69]
	v_pk_mul_f32 v[20:21], v[20:21], v[68:69]
	v_pk_mul_f32 v[4:5], v[4:5], v[68:69]
	v_pk_mul_f32 v[70:71], v[50:51], v[50:51]
	v_pk_mul_f32 v[72:73], v[52:53], v[52:53]
	v_pk_fma_f32 v[70:71], v[34:35], v[34:35], v[70:71]
	v_pk_fma_f32 v[72:73], v[36:37], v[36:37], v[72:73]
	v_pk_fma_f32 v[70:71], v[18:19], v[18:19], v[70:71]
	v_pk_fma_f32 v[72:73], v[20:21], v[20:21], v[72:73]
	v_pk_fma_f32 v[70:71], v[2:3], v[2:3], v[70:71]
	v_pk_fma_f32 v[72:73], v[4:5], v[4:5], v[72:73]
	s_nop 1
	v_add_f32_dpp v70, v70, v70 quad_perm:[1,0,3,2] row_mask:0xf bank_mask:0xf
	v_add_f32_dpp v71, v71, v71 quad_perm:[1,0,3,2] row_mask:0xf bank_mask:0xf
	v_add_f32_dpp v72, v72, v72 quad_perm:[1,0,3,2] row_mask:0xf bank_mask:0xf
	v_add_f32_dpp v73, v73, v73 quad_perm:[1,0,3,2] row_mask:0xf bank_mask:0xf
	v_add_f32_dpp v70, v70, v70 quad_perm:[2,3,0,1] row_mask:0xf bank_mask:0xf
	v_add_f32_dpp v71, v71, v71 quad_perm:[2,3,0,1] row_mask:0xf bank_mask:0xf
	v_add_f32_dpp v72, v72, v72 quad_perm:[2,3,0,1] row_mask:0xf bank_mask:0xf
	v_add_f32_dpp v73, v73, v73 quad_perm:[2,3,0,1] row_mask:0xf bank_mask:0xf
	v_add_f32_dpp v70, v70, v70 row_half_mirror row_mask:0xf bank_mask:0xf
	v_add_f32_dpp v71, v71, v71 row_half_mirror row_mask:0xf bank_mask:0xf
	v_add_f32_dpp v72, v72, v72 row_half_mirror row_mask:0xf bank_mask:0xf
	v_add_f32_dpp v73, v73, v73 row_half_mirror row_mask:0xf bank_mask:0xf
	v_add_f32_dpp v70, v70, v70 row_mirror row_mask:0xf bank_mask:0xf
	v_add_f32_dpp v71, v71, v71 row_mirror row_mask:0xf bank_mask:0xf
	v_add_f32_dpp v72, v72, v72 row_mirror row_mask:0xf bank_mask:0xf
	v_add_f32_dpp v73, v73, v73 row_mirror row_mask:0xf bank_mask:0xf
	v_mov_b32_e32 v74, v70
	v_mov_b32_e32 v75, v71
	v_mov_b32_e32 v76, v72
	v_mov_b32_e32 v77, v73
	v_permlane16_swap_b32_e32 v70, v74
	v_permlane16_swap_b32_e32 v71, v75
	v_permlane16_swap_b32_e32 v72, v76
	v_permlane16_swap_b32_e32 v73, v77
	v_add_f32_e32 v70, v70, v74
	v_add_f32_e32 v71, v71, v75
	v_add_f32_e32 v72, v72, v76
	v_add_f32_e32 v73, v73, v77
	v_fmamk_f32 v70, v70, 0x3c000000, v192
	v_fmamk_f32 v71, v71, 0x3c000000, v192
	v_fmamk_f32 v72, v72, 0x3c000000, v192
	v_fmamk_f32 v73, v73, 0x3c000000, v192
	v_rsq_f32_e32 v70, v70
	v_rsq_f32_e32 v71, v71
	v_rsq_f32_e32 v72, v72
	v_rsq_f32_e32 v73, v73
	s_nop 0
	v_pk_mul_f32 v[50:51], v[50:51], v[70:71]
	v_pk_mul_f32 v[34:35], v[34:35], v[70:71]
	v_pk_mul_f32 v[18:19], v[18:19], v[70:71]
	v_pk_mul_f32 v[2:3], v[2:3], v[70:71]
	v_pk_mul_f32 v[52:53], v[52:53], v[72:73]
	v_pk_mul_f32 v[36:37], v[36:37], v[72:73]
	v_pk_mul_f32 v[20:21], v[20:21], v[72:73]
	v_pk_mul_f32 v[4:5], v[4:5], v[72:73]
	s_nop 0
	v_mov_b32_dpp v74, v50 quad_perm:[1,0,3,2] row_mask:0xf bank_mask:0xf
	v_mov_b32_dpp v75, v34 quad_perm:[1,0,3,2] row_mask:0xf bank_mask:0xf
	v_mov_b32_dpp v76, v18 quad_perm:[1,0,3,2] row_mask:0xf bank_mask:0xf
	v_mov_b32_dpp v77, v2 quad_perm:[1,0,3,2] row_mask:0xf bank_mask:0xf
	v_cvt_pk_bf16_f32 v50, v50, v74
	v_cvt_pk_bf16_f32 v34, v34, v75
	v_cvt_pk_bf16_f32 v18, v18, v76
	v_cvt_pk_bf16_f32 v2, v2, v77
	v_mov_b32_dpp v74, v51 quad_perm:[1,0,3,2] row_mask:0xf bank_mask:0xf
	v_mov_b32_dpp v75, v35 quad_perm:[1,0,3,2] row_mask:0xf bank_mask:0xf
	v_mov_b32_dpp v76, v19 quad_perm:[1,0,3,2] row_mask:0xf bank_mask:0xf
	v_mov_b32_dpp v77, v3 quad_perm:[1,0,3,2] row_mask:0xf bank_mask:0xf
	v_cvt_pk_bf16_f32 v51, v51, v74
	v_cvt_pk_bf16_f32 v35, v35, v75
	v_cvt_pk_bf16_f32 v19, v19, v76
	v_cvt_pk_bf16_f32 v3, v3, v77
	v_mov_b32_dpp v74, v52 quad_perm:[1,0,3,2] row_mask:0xf bank_mask:0xf
	v_mov_b32_dpp v75, v36 quad_perm:[1,0,3,2] row_mask:0xf bank_mask:0xf
	v_mov_b32_dpp v76, v20 quad_perm:[1,0,3,2] row_mask:0xf bank_mask:0xf
	v_mov_b32_dpp v77, v4 quad_perm:[1,0,3,2] row_mask:0xf bank_mask:0xf
	v_cvt_pk_bf16_f32 v52, v52, v74
	v_cvt_pk_bf16_f32 v36, v36, v75
	v_cvt_pk_bf16_f32 v20, v20, v76
	v_cvt_pk_bf16_f32 v4, v4, v77
	v_mov_b32_dpp v74, v53 quad_perm:[1,0,3,2] row_mask:0xf bank_mask:0xf
	v_mov_b32_dpp v75, v37 quad_perm:[1,0,3,2] row_mask:0xf bank_mask:0xf
	v_mov_b32_dpp v76, v21 quad_perm:[1,0,3,2] row_mask:0xf bank_mask:0xf
	v_mov_b32_dpp v77, v5 quad_perm:[1,0,3,2] row_mask:0xf bank_mask:0xf
	v_cvt_pk_bf16_f32 v53, v53, v74
	v_cvt_pk_bf16_f32 v37, v37, v75
	v_cvt_pk_bf16_f32 v21, v21, v76
	v_cvt_pk_bf16_f32 v5, v5, v77
	ds_read_b32 v66, v218 offset:32
	ds_read_b32 v67, v218 offset:36
	ds_read_b32 v68, v218 offset:40
	ds_read_b32 v69, v218 offset:44
	s_waitcnt lgkmcnt(0)
; __device__ __forceinline__ unsigned cvt_pk_bf16(float lo, float hi) { unsigned r; asm volatile("v_cvt_pk_bf16_f32 %0, %1, %2" : "=v"(r) : "v"(lo), "v"(hi)); return r; }
; __device__ __forceinline__ int crow(int r, int hi) { return (r & 3) + 8 * (r >> 2) + 4 * hi; }
; __device__ __forceinline__ void block(const BlockRef& cur, const int j0, const int NT, const int split, const SplitRef sp, lptr lds, int tid) {
;     ...
;     for (int r = 0; r < 16; ++r) { const int orow = crow(r, hi); const float rli = __builtin_amdgcn_rcpf(li_l[orow]);
;         float v0 = o[0][r] * rli, v1 = o[1][r] * rli, v2 = o[2][r] * rli, v3 = o[3][r] * rli;
;         float ss = (v0 * v0 + v1 * v1) + (v2 * v2 + v3 * v3);
;         ss += __shfl_xor(ss, 1); ss += __shfl_xor(ss, 2); ss += __shfl_xor(ss, 4); ss += __shfl_xor(ss, 8); ss += __shfl_xor(ss, 16);
;         const float rs = rsqrtf(ss * (1.0f / 128.0f) + EPS);
;         v0 *= rs; v1 *= rs; v2 *= rs; v3 *= rs;
;         const float n0 = __shfl_xor(v0, 1), n1 = __shfl_xor(v1, 1), n2 = __shfl_xor(v2, 1), n3 = __shfl_xor(v3, 1);
;         if ((r32 & 1) == 0) { bf16_t* op = Ow + (size_t)orow * DM + r32;
;             *(unsigned*)(op) = cvt_pk_bf16(v0, n0); *(unsigned*)(op + 32) = cvt_pk_bf16(v1, n1); *(unsigned*)(op + 64) = cvt_pk_bf16(v2, n2); *(unsigned*)(op + 96) = cvt_pk_bf16(v3, n3); } }
	v_rcp_f32_e32 v66, v66
	v_rcp_f32_e32 v67, v67
	v_rcp_f32_e32 v68, v68
	v_rcp_f32_e32 v69, v69
	v_pk_mul_f32 v[54:55], v[54:55], v[66:67]
	v_pk_mul_f32 v[38:39], v[38:39], v[66:67]
	v_pk_mul_f32 v[22:23], v[22:23], v[66:67]
	v_pk_mul_f32 v[6:7], v[6:7], v[66:67]
	v_pk_mul_f32 v[56:57], v[56:57], v[68:69]
	v_pk_mul_f32 v[40:41], v[40:41], v[68:69]
	v_pk_mul_f32 v[24:25], v[24:25], v[68:69]
	v_pk_mul_f32 v[8:9], v[8:9], v[68:69]
	v_pk_mul_f32 v[70:71], v[54:55], v[54:55]
	v_pk_mul_f32 v[72:73], v[56:57], v[56:57]
	v_pk_fma_f32 v[70:71], v[38:39], v[38:39], v[70:71]
	v_pk_fma_f32 v[72:73], v[40:41], v[40:41], v[72:73]
	v_pk_fma_f32 v[70:71], v[22:23], v[22:23], v[70:71]
	v_pk_fma_f32 v[72:73], v[24:25], v[24:25], v[72:73]
	v_pk_fma_f32 v[70:71], v[6:7], v[6:7], v[70:71]
	v_pk_fma_f32 v[72:73], v[8:9], v[8:9], v[72:73]
	s_nop 1
	v_add_f32_dpp v70, v70, v70 quad_perm:[1,0,3,2] row_mask:0xf bank_mask:0xf
	v_add_f32_dpp v71, v71, v71 quad_perm:[1,0,3,2] row_mask:0xf bank_mask:0xf
	v_add_f32_dpp v72, v72, v72 quad_perm:[1,0,3,2] row_mask:0xf bank_mask:0xf
	v_add_f32_dpp v73, v73, v73 quad_perm:[1,0,3,2] row_mask:0xf bank_mask:0xf
	v_add_f32_dpp v70, v70, v70 quad_perm:[2,3,0,1] row_mask:0xf bank_mask:0xf
	v_add_f32_dpp v71, v71, v71 quad_perm:[2,3,0,1] row_mask:0xf bank_mask:0xf
	v_add_f32_dpp v72, v72, v72 quad_perm:[2,3,0,1] row_mask:0xf bank_mask:0xf
	v_add_f32_dpp v73, v73, v73 quad_perm:[2,3,0,1] row_mask:0xf bank_mask:0xf
	v_add_f32_dpp v70, v70, v70 row_half_mirror row_mask:0xf bank_mask:0xf
	v_add_f32_dpp v71, v71, v71 row_half_mirror row_mask:0xf bank_mask:0xf
	v_add_f32_dpp v72, v72, v72 row_half_mirror row_mask:0xf bank_mask:0xf
	v_add_f32_dpp v73, v73, v73 row_half_mirror row_mask:0xf bank_mask:0xf
	v_add_f32_dpp v70, v70, v70 row_mirror row_mask:0xf bank_mask:0xf
	v_add_f32_dpp v71, v71, v71 row_mirror row_mask:0xf bank_mask:0xf
	v_add_f32_dpp v72, v72, v72 row_mirror row_mask:0xf bank_mask:0xf
	v_add_f32_dpp v73, v73, v73 row_mirror row_mask:0xf bank_mask:0xf
	v_mov_b32_e32 v74, v70
	v_mov_b32_e32 v75, v71
	v_mov_b32_e32 v76, v72
	v_mov_b32_e32 v77, v73
	v_permlane16_swap_b32_e32 v70, v74
	v_permlane16_swap_b32_e32 v71, v75
	v_permlane16_swap_b32_e32 v72, v76
	v_permlane16_swap_b32_e32 v73, v77
	v_add_f32_e32 v70, v70, v74
	v_add_f32_e32 v71, v71, v75
	v_add_f32_e32 v72, v72, v76
	v_add_f32_e32 v73, v73, v77
	v_fmamk_f32 v70, v70, 0x3c000000, v192
	v_fmamk_f32 v71, v71, 0x3c000000, v192
	v_fmamk_f32 v72, v72, 0x3c000000, v192
	v_fmamk_f32 v73, v73, 0x3c000000, v192
	v_rsq_f32_e32 v70, v70
	v_rsq_f32_e32 v71, v71
	v_rsq_f32_e32 v72, v72
	v_rsq_f32_e32 v73, v73
	s_nop 0
	v_pk_mul_f32 v[54:55], v[54:55], v[70:71]
	v_pk_mul_f32 v[38:39], v[38:39], v[70:71]
	v_pk_mul_f32 v[22:23], v[22:23], v[70:71]
	v_pk_mul_f32 v[6:7], v[6:7], v[70:71]
	v_pk_mul_f32 v[56:57], v[56:57], v[72:73]
	v_pk_mul_f32 v[40:41], v[40:41], v[72:73]
	v_pk_mul_f32 v[24:25], v[24:25], v[72:73]
	v_pk_mul_f32 v[8:9], v[8:9], v[72:73]
	s_nop 0
	v_mov_b32_dpp v74, v54 quad_perm:[1,0,3,2] row_mask:0xf bank_mask:0xf
	v_mov_b32_dpp v75, v38 quad_perm:[1,0,3,2] row_mask:0xf bank_mask:0xf
	v_mov_b32_dpp v76, v22 quad_perm:[1,0,3,2] row_mask:0xf bank_mask:0xf
	v_mov_b32_dpp v77, v6 quad_perm:[1,0,3,2] row_mask:0xf bank_mask:0xf
	v_cvt_pk_bf16_f32 v54, v54, v74
	v_cvt_pk_bf16_f32 v38, v38, v75
	v_cvt_pk_bf16_f32 v22, v22, v76
	v_cvt_pk_bf16_f32 v6, v6, v77
	v_mov_b32_dpp v74, v55 quad_perm:[1,0,3,2] row_mask:0xf bank_mask:0xf
	v_mov_b32_dpp v75, v39 quad_perm:[1,0,3,2] row_mask:0xf bank_mask:0xf
	v_mov_b32_dpp v76, v23 quad_perm:[1,0,3,2] row_mask:0xf bank_mask:0xf
	v_mov_b32_dpp v77, v7 quad_perm:[1,0,3,2] row_mask:0xf bank_mask:0xf
	v_cvt_pk_bf16_f32 v55, v55, v74
	v_cvt_pk_bf16_f32 v39, v39, v75
	v_cvt_pk_bf16_f32 v23, v23, v76
	v_cvt_pk_bf16_f32 v7, v7, v77
	v_mov_b32_dpp v74, v56 quad_perm:[1,0,3,2] row_mask:0xf bank_mask:0xf
	v_mov_b32_dpp v75, v40 quad_perm:[1,0,3,2] row_mask:0xf bank_mask:0xf
	v_mov_b32_dpp v76, v24 quad_perm:[1,0,3,2] row_mask:0xf bank_mask:0xf
	v_mov_b32_dpp v77, v8 quad_perm:[1,0,3,2] row_mask:0xf bank_mask:0xf
	v_cvt_pk_bf16_f32 v56, v56, v74
	v_cvt_pk_bf16_f32 v40, v40, v75
	v_cvt_pk_bf16_f32 v24, v24, v76
	v_cvt_pk_bf16_f32 v8, v8, v77
	v_mov_b32_dpp v74, v57 quad_perm:[1,0,3,2] row_mask:0xf bank_mask:0xf
	v_mov_b32_dpp v75, v41 quad_perm:[1,0,3,2] row_mask:0xf bank_mask:0xf
	v_mov_b32_dpp v76, v25 quad_perm:[1,0,3,2] row_mask:0xf bank_mask:0xf
	v_mov_b32_dpp v77, v9 quad_perm:[1,0,3,2] row_mask:0xf bank_mask:0xf
	v_cvt_pk_bf16_f32 v57, v57, v74
	v_cvt_pk_bf16_f32 v41, v41, v75
	v_cvt_pk_bf16_f32 v25, v25, v76
	v_cvt_pk_bf16_f32 v9, v9, v77
	ds_read_b32 v66, v218 offset:64
	ds_read_b32 v67, v218 offset:68
	ds_read_b32 v68, v218 offset:72
	ds_read_b32 v69, v218 offset:76
	s_waitcnt lgkmcnt(0)
; __device__ __forceinline__ unsigned cvt_pk_bf16(float lo, float hi) { unsigned r; asm volatile("v_cvt_pk_bf16_f32 %0, %1, %2" : "=v"(r) : "v"(lo), "v"(hi)); return r; }
; __device__ __forceinline__ int crow(int r, int hi) { return (r & 3) + 8 * (r >> 2) + 4 * hi; }
; __device__ __forceinline__ void block(const BlockRef& cur, const int j0, const int NT, const int split, const SplitRef sp, lptr lds, int tid) {
;     ...
;     for (int r = 0; r < 16; ++r) { const int orow = crow(r, hi); const float rli = __builtin_amdgcn_rcpf(li_l[orow]);
;         float v0 = o[0][r] * rli, v1 = o[1][r] * rli, v2 = o[2][r] * rli, v3 = o[3][r] * rli;
;         float ss = (v0 * v0 + v1 * v1) + (v2 * v2 + v3 * v3);
;         ss += __shfl_xor(ss, 1); ss += __shfl_xor(ss, 2); ss += __shfl_xor(ss, 4); ss += __shfl_xor(ss, 8); ss += __shfl_xor(ss, 16);
;         const float rs = rsqrtf(ss * (1.0f / 128.0f) + EPS);
;         v0 *= rs; v1 *= rs; v2 *= rs; v3 *= rs;
;         const float n0 = __shfl_xor(v0, 1), n1 = __shfl_xor(v1, 1), n2 = __shfl_xor(v2, 1), n3 = __shfl_xor(v3, 1);
;         if ((r32 & 1) == 0) { bf16_t* op = Ow + (size_t)orow * DM + r32;
;             *(unsigned*)(op) = cvt_pk_bf16(v0, n0); *(unsigned*)(op + 32) = cvt_pk_bf16(v1, n1); *(unsigned*)(op + 64) = cvt_pk_bf16(v2, n2); *(unsigned*)(op + 96) = cvt_pk_bf16(v3, n3); } }
	v_rcp_f32_e32 v66, v66
	v_rcp_f32_e32 v67, v67
	v_rcp_f32_e32 v68, v68
	v_rcp_f32_e32 v69, v69
	v_pk_mul_f32 v[58:59], v[58:59], v[66:67]
	v_pk_mul_f32 v[42:43], v[42:43], v[66:67]
	v_pk_mul_f32 v[26:27], v[26:27], v[66:67]
	v_pk_mul_f32 v[10:11], v[10:11], v[66:67]
	v_pk_mul_f32 v[60:61], v[60:61], v[68:69]
	v_pk_mul_f32 v[44:45], v[44:45], v[68:69]
	v_pk_mul_f32 v[28:29], v[28:29], v[68:69]
	v_pk_mul_f32 v[12:13], v[12:13], v[68:69]
	v_pk_mul_f32 v[70:71], v[58:59], v[58:59]
	v_pk_mul_f32 v[72:73], v[60:61], v[60:61]
	v_pk_fma_f32 v[70:71], v[42:43], v[42:43], v[70:71]
	v_pk_fma_f32 v[72:73], v[44:45], v[44:45], v[72:73]
	v_pk_fma_f32 v[70:71], v[26:27], v[26:27], v[70:71]
	v_pk_fma_f32 v[72:73], v[28:29], v[28:29], v[72:73]
	v_pk_fma_f32 v[70:71], v[10:11], v[10:11], v[70:71]
	v_pk_fma_f32 v[72:73], v[12:13], v[12:13], v[72:73]
	s_nop 1
	v_add_f32_dpp v70, v70, v70 quad_perm:[1,0,3,2] row_mask:0xf bank_mask:0xf
	v_add_f32_dpp v71, v71, v71 quad_perm:[1,0,3,2] row_mask:0xf bank_mask:0xf
	v_add_f32_dpp v72, v72, v72 quad_perm:[1,0,3,2] row_mask:0xf bank_mask:0xf
	v_add_f32_dpp v73, v73, v73 quad_perm:[1,0,3,2] row_mask:0xf bank_mask:0xf
	v_add_f32_dpp v70, v70, v70 quad_perm:[2,3,0,1] row_mask:0xf bank_mask:0xf
	v_add_f32_dpp v71, v71, v71 quad_perm:[2,3,0,1] row_mask:0xf bank_mask:0xf
	v_add_f32_dpp v72, v72, v72 quad_perm:[2,3,0,1] row_mask:0xf bank_mask:0xf
	v_add_f32_dpp v73, v73, v73 quad_perm:[2,3,0,1] row_mask:0xf bank_mask:0xf
	v_add_f32_dpp v70, v70, v70 row_half_mirror row_mask:0xf bank_mask:0xf
	v_add_f32_dpp v71, v71, v71 row_half_mirror row_mask:0xf bank_mask:0xf
	v_add_f32_dpp v72, v72, v72 row_half_mirror row_mask:0xf bank_mask:0xf
	v_add_f32_dpp v73, v73, v73 row_half_mirror row_mask:0xf bank_mask:0xf
	v_add_f32_dpp v70, v70, v70 row_mirror row_mask:0xf bank_mask:0xf
	v_add_f32_dpp v71, v71, v71 row_mirror row_mask:0xf bank_mask:0xf
	v_add_f32_dpp v72, v72, v72 row_mirror row_mask:0xf bank_mask:0xf
	v_add_f32_dpp v73, v73, v73 row_mirror row_mask:0xf bank_mask:0xf
	v_mov_b32_e32 v74, v70
	v_mov_b32_e32 v75, v71
	v_mov_b32_e32 v76, v72
	v_mov_b32_e32 v77, v73
	v_permlane16_swap_b32_e32 v70, v74
	v_permlane16_swap_b32_e32 v71, v75
	v_permlane16_swap_b32_e32 v72, v76
	v_permlane16_swap_b32_e32 v73, v77
	v_add_f32_e32 v70, v70, v74
	v_add_f32_e32 v71, v71, v75
	v_add_f32_e32 v72, v72, v76
	v_add_f32_e32 v73, v73, v77
	v_fmamk_f32 v70, v70, 0x3c000000, v192
	v_fmamk_f32 v71, v71, 0x3c000000, v192
	v_fmamk_f32 v72, v72, 0x3c000000, v192
	v_fmamk_f32 v73, v73, 0x3c000000, v192
	v_rsq_f32_e32 v70, v70
	v_rsq_f32_e32 v71, v71
	v_rsq_f32_e32 v72, v72
	v_rsq_f32_e32 v73, v73
	s_nop 0
	v_pk_mul_f32 v[58:59], v[58:59], v[70:71]
	v_pk_mul_f32 v[42:43], v[42:43], v[70:71]
	v_pk_mul_f32 v[26:27], v[26:27], v[70:71]
	v_pk_mul_f32 v[10:11], v[10:11], v[70:71]
	v_pk_mul_f32 v[60:61], v[60:61], v[72:73]
	v_pk_mul_f32 v[44:45], v[44:45], v[72:73]
	v_pk_mul_f32 v[28:29], v[28:29], v[72:73]
	v_pk_mul_f32 v[12:13], v[12:13], v[72:73]
	s_nop 0
	v_mov_b32_dpp v74, v58 quad_perm:[1,0,3,2] row_mask:0xf bank_mask:0xf
	v_mov_b32_dpp v75, v42 quad_perm:[1,0,3,2] row_mask:0xf bank_mask:0xf
	v_mov_b32_dpp v76, v26 quad_perm:[1,0,3,2] row_mask:0xf bank_mask:0xf
	v_mov_b32_dpp v77, v10 quad_perm:[1,0,3,2] row_mask:0xf bank_mask:0xf
	v_cvt_pk_bf16_f32 v58, v58, v74
	v_cvt_pk_bf16_f32 v42, v42, v75
	v_cvt_pk_bf16_f32 v26, v26, v76
	v_cvt_pk_bf16_f32 v10, v10, v77
	v_mov_b32_dpp v74, v59 quad_perm:[1,0,3,2] row_mask:0xf bank_mask:0xf
	v_mov_b32_dpp v75, v43 quad_perm:[1,0,3,2] row_mask:0xf bank_mask:0xf
	v_mov_b32_dpp v76, v27 quad_perm:[1,0,3,2] row_mask:0xf bank_mask:0xf
	v_mov_b32_dpp v77, v11 quad_perm:[1,0,3,2] row_mask:0xf bank_mask:0xf
	v_cvt_pk_bf16_f32 v59, v59, v74
	v_cvt_pk_bf16_f32 v43, v43, v75
	v_cvt_pk_bf16_f32 v27, v27, v76
	v_cvt_pk_bf16_f32 v11, v11, v77
	v_mov_b32_dpp v74, v60 quad_perm:[1,0,3,2] row_mask:0xf bank_mask:0xf
	v_mov_b32_dpp v75, v44 quad_perm:[1,0,3,2] row_mask:0xf bank_mask:0xf
	v_mov_b32_dpp v76, v28 quad_perm:[1,0,3,2] row_mask:0xf bank_mask:0xf
	v_mov_b32_dpp v77, v12 quad_perm:[1,0,3,2] row_mask:0xf bank_mask:0xf
	v_cvt_pk_bf16_f32 v60, v60, v74
	v_cvt_pk_bf16_f32 v44, v44, v75
	v_cvt_pk_bf16_f32 v28, v28, v76
	v_cvt_pk_bf16_f32 v12, v12, v77
	v_mov_b32_dpp v74, v61 quad_perm:[1,0,3,2] row_mask:0xf bank_mask:0xf
	v_mov_b32_dpp v75, v45 quad_perm:[1,0,3,2] row_mask:0xf bank_mask:0xf
	v_mov_b32_dpp v76, v29 quad_perm:[1,0,3,2] row_mask:0xf bank_mask:0xf
	v_mov_b32_dpp v77, v13 quad_perm:[1,0,3,2] row_mask:0xf bank_mask:0xf
	v_cvt_pk_bf16_f32 v61, v61, v74
	v_cvt_pk_bf16_f32 v45, v45, v75
	v_cvt_pk_bf16_f32 v29, v29, v76
	v_cvt_pk_bf16_f32 v13, v13, v77
	ds_read_b32 v66, v218 offset:96
	ds_read_b32 v67, v218 offset:100
	ds_read_b32 v68, v218 offset:104
	ds_read_b32 v69, v218 offset:108
	s_waitcnt lgkmcnt(0)
; __device__ __forceinline__ unsigned cvt_pk_bf16(float lo, float hi) { unsigned r; asm volatile("v_cvt_pk_bf16_f32 %0, %1, %2" : "=v"(r) : "v"(lo), "v"(hi)); return r; }
; __device__ __forceinline__ int crow(int r, int hi) { return (r & 3) + 8 * (r >> 2) + 4 * hi; }
; __device__ __forceinline__ void block(const BlockRef& cur, const int j0, const int NT, const int split, const SplitRef sp, lptr lds, int tid) {
;     ...
;     for (int r = 0; r < 16; ++r) { const int orow = crow(r, hi); const float rli = __builtin_amdgcn_rcpf(li_l[orow]);
;         float v0 = o[0][r] * rli, v1 = o[1][r] * rli, v2 = o[2][r] * rli, v3 = o[3][r] * rli;
;         float ss = (v0 * v0 + v1 * v1) + (v2 * v2 + v3 * v3);
;         ss += __shfl_xor(ss, 1); ss += __shfl_xor(ss, 2); ss += __shfl_xor(ss, 4); ss += __shfl_xor(ss, 8); ss += __shfl_xor(ss, 16);
;         const float rs = rsqrtf(ss * (1.0f / 128.0f) + EPS);
;         v0 *= rs; v1 *= rs; v2 *= rs; v3 *= rs;
;         const float n0 = __shfl_xor(v0, 1), n1 = __shfl_xor(v1, 1), n2 = __shfl_xor(v2, 1), n3 = __shfl_xor(v3, 1);
;         if ((r32 & 1) == 0) { bf16_t* op = Ow + (size_t)orow * DM + r32;
;             *(unsigned*)(op) = cvt_pk_bf16(v0, n0); *(unsigned*)(op + 32) = cvt_pk_bf16(v1, n1); *(unsigned*)(op + 64) = cvt_pk_bf16(v2, n2); *(unsigned*)(op + 96) = cvt_pk_bf16(v3, n3); } }
	v_rcp_f32_e32 v66, v66
	v_rcp_f32_e32 v67, v67
	v_rcp_f32_e32 v68, v68
	v_rcp_f32_e32 v69, v69
	v_pk_mul_f32 v[62:63], v[62:63], v[66:67]
	v_pk_mul_f32 v[46:47], v[46:47], v[66:67]
	v_pk_mul_f32 v[30:31], v[30:31], v[66:67]
	v_pk_mul_f32 v[14:15], v[14:15], v[66:67]
	v_pk_mul_f32 v[64:65], v[64:65], v[68:69]
	v_pk_mul_f32 v[48:49], v[48:49], v[68:69]
	v_pk_mul_f32 v[32:33], v[32:33], v[68:69]
	v_pk_mul_f32 v[16:17], v[16:17], v[68:69]
	v_pk_mul_f32 v[70:71], v[62:63], v[62:63]
	v_pk_mul_f32 v[72:73], v[64:65], v[64:65]
	v_pk_fma_f32 v[70:71], v[46:47], v[46:47], v[70:71]
	v_pk_fma_f32 v[72:73], v[48:49], v[48:49], v[72:73]
	v_pk_fma_f32 v[70:71], v[30:31], v[30:31], v[70:71]
	v_pk_fma_f32 v[72:73], v[32:33], v[32:33], v[72:73]
	v_pk_fma_f32 v[70:71], v[14:15], v[14:15], v[70:71]
	v_pk_fma_f32 v[72:73], v[16:17], v[16:17], v[72:73]
	s_nop 1
	v_add_f32_dpp v70, v70, v70 quad_perm:[1,0,3,2] row_mask:0xf bank_mask:0xf
	v_add_f32_dpp v71, v71, v71 quad_perm:[1,0,3,2] row_mask:0xf bank_mask:0xf
	v_add_f32_dpp v72, v72, v72 quad_perm:[1,0,3,2] row_mask:0xf bank_mask:0xf
	v_add_f32_dpp v73, v73, v73 quad_perm:[1,0,3,2] row_mask:0xf bank_mask:0xf
	v_add_f32_dpp v70, v70, v70 quad_perm:[2,3,0,1] row_mask:0xf bank_mask:0xf
	v_add_f32_dpp v71, v71, v71 quad_perm:[2,3,0,1] row_mask:0xf bank_mask:0xf
	v_add_f32_dpp v72, v72, v72 quad_perm:[2,3,0,1] row_mask:0xf bank_mask:0xf
	v_add_f32_dpp v73, v73, v73 quad_perm:[2,3,0,1] row_mask:0xf bank_mask:0xf
	v_add_f32_dpp v70, v70, v70 row_half_mirror row_mask:0xf bank_mask:0xf
	v_add_f32_dpp v71, v71, v71 row_half_mirror row_mask:0xf bank_mask:0xf
	v_add_f32_dpp v72, v72, v72 row_half_mirror row_mask:0xf bank_mask:0xf
	v_add_f32_dpp v73, v73, v73 row_half_mirror row_mask:0xf bank_mask:0xf
	v_add_f32_dpp v70, v70, v70 row_mirror row_mask:0xf bank_mask:0xf
	v_add_f32_dpp v71, v71, v71 row_mirror row_mask:0xf bank_mask:0xf
	v_add_f32_dpp v72, v72, v72 row_mirror row_mask:0xf bank_mask:0xf
	v_add_f32_dpp v73, v73, v73 row_mirror row_mask:0xf bank_mask:0xf
	v_mov_b32_e32 v74, v70
	v_mov_b32_e32 v75, v71
	v_mov_b32_e32 v76, v72
	v_mov_b32_e32 v77, v73
	v_permlane16_swap_b32_e32 v70, v74
	v_permlane16_swap_b32_e32 v71, v75
	v_permlane16_swap_b32_e32 v72, v76
	v_permlane16_swap_b32_e32 v73, v77
	v_add_f32_e32 v70, v70, v74
	v_add_f32_e32 v71, v71, v75
	v_add_f32_e32 v72, v72, v76
	v_add_f32_e32 v73, v73, v77
	v_fmamk_f32 v70, v70, 0x3c000000, v192
	v_fmamk_f32 v71, v71, 0x3c000000, v192
	v_fmamk_f32 v72, v72, 0x3c000000, v192
	v_fmamk_f32 v73, v73, 0x3c000000, v192
	v_rsq_f32_e32 v70, v70
	v_rsq_f32_e32 v71, v71
	v_rsq_f32_e32 v72, v72
	v_rsq_f32_e32 v73, v73
	s_nop 0
	v_pk_mul_f32 v[62:63], v[62:63], v[70:71]
	v_pk_mul_f32 v[46:47], v[46:47], v[70:71]
	v_pk_mul_f32 v[30:31], v[30:31], v[70:71]
	v_pk_mul_f32 v[14:15], v[14:15], v[70:71]
	v_pk_mul_f32 v[64:65], v[64:65], v[72:73]
	v_pk_mul_f32 v[48:49], v[48:49], v[72:73]
	v_pk_mul_f32 v[32:33], v[32:33], v[72:73]
	v_pk_mul_f32 v[16:17], v[16:17], v[72:73]
	s_nop 0
	v_mov_b32_dpp v74, v62 quad_perm:[1,0,3,2] row_mask:0xf bank_mask:0xf
	v_mov_b32_dpp v75, v46 quad_perm:[1,0,3,2] row_mask:0xf bank_mask:0xf
	v_mov_b32_dpp v76, v30 quad_perm:[1,0,3,2] row_mask:0xf bank_mask:0xf
	v_mov_b32_dpp v77, v14 quad_perm:[1,0,3,2] row_mask:0xf bank_mask:0xf
	v_cvt_pk_bf16_f32 v62, v62, v74
	v_cvt_pk_bf16_f32 v46, v46, v75
	v_cvt_pk_bf16_f32 v30, v30, v76
	v_cvt_pk_bf16_f32 v14, v14, v77
	v_mov_b32_dpp v74, v63 quad_perm:[1,0,3,2] row_mask:0xf bank_mask:0xf
	v_mov_b32_dpp v75, v47 quad_perm:[1,0,3,2] row_mask:0xf bank_mask:0xf
	v_mov_b32_dpp v76, v31 quad_perm:[1,0,3,2] row_mask:0xf bank_mask:0xf
	v_mov_b32_dpp v77, v15 quad_perm:[1,0,3,2] row_mask:0xf bank_mask:0xf
	v_cvt_pk_bf16_f32 v63, v63, v74
	v_cvt_pk_bf16_f32 v47, v47, v75
	v_cvt_pk_bf16_f32 v31, v31, v76
	v_cvt_pk_bf16_f32 v15, v15, v77
	v_mov_b32_dpp v74, v64 quad_perm:[1,0,3,2] row_mask:0xf bank_mask:0xf
	v_mov_b32_dpp v75, v48 quad_perm:[1,0,3,2] row_mask:0xf bank_mask:0xf
	v_mov_b32_dpp v76, v32 quad_perm:[1,0,3,2] row_mask:0xf bank_mask:0xf
	v_mov_b32_dpp v77, v16 quad_perm:[1,0,3,2] row_mask:0xf bank_mask:0xf
	v_cvt_pk_bf16_f32 v64, v64, v74
	v_cvt_pk_bf16_f32 v48, v48, v75
	v_cvt_pk_bf16_f32 v32, v32, v76
	v_cvt_pk_bf16_f32 v16, v16, v77
	v_mov_b32_dpp v74, v65 quad_perm:[1,0,3,2] row_mask:0xf bank_mask:0xf
	v_mov_b32_dpp v75, v49 quad_perm:[1,0,3,2] row_mask:0xf bank_mask:0xf
	v_mov_b32_dpp v76, v33 quad_perm:[1,0,3,2] row_mask:0xf bank_mask:0xf
	v_mov_b32_dpp v77, v17 quad_perm:[1,0,3,2] row_mask:0xf bank_mask:0xf
	v_cvt_pk_bf16_f32 v65, v65, v74
	v_cvt_pk_bf16_f32 v49, v49, v75
	v_cvt_pk_bf16_f32 v33, v33, v76
	v_cvt_pk_bf16_f32 v17, v17, v77
	s_lshr_b32 s6, s0, 5
	s_add_i32 s6, s6, 0x15000
	v_lshlrev_b32_e32 v66, 1, v219
	v_and_b32_e32 v68, 63, v174
	v_lshl_add_u32 v66, v217, 9, v66
	v_lshlrev_b32_e32 v67, 4, v68
	v_lshrrev_b32_e32 v69, 3, v68
	v_and_b32_e32 v68, 7, v68
	v_add_u32_e32 v66, s6, v66
	v_lshlrev_b32_e32 v68, 4, v68
	v_add_u32_e32 v67, s6, v67
	v_lshl_add_u32 v162, v69, 12, v68
	s_mov_b64 s[0:1], exec
	s_and_b64 exec, s[0:1], vcc
	ds_write_b32 v66, v50
	ds_write_b32 v66, v51 offset:128
	ds_write_b32 v66, v52 offset:256
	ds_write_b32 v66, v53 offset:384
	ds_write_b32 v66, v54 offset:1024
	ds_write_b32 v66, v55 offset:1152
	ds_write_b32 v66, v56 offset:1280
	ds_write_b32 v66, v57 offset:1408
	ds_write_b32 v66, v58 offset:2048
	ds_write_b32 v66, v59 offset:2176
	ds_write_b32 v66, v60 offset:2304
	ds_write_b32 v66, v61 offset:2432
	ds_write_b32 v66, v62 offset:3072
	ds_write_b32 v66, v63 offset:3200
	ds_write_b32 v66, v64 offset:3328
	ds_write_b32 v66, v65 offset:3456
	ds_write_b32 v66, v34 offset:64
	ds_write_b32 v66, v35 offset:192
	ds_write_b32 v66, v36 offset:320
	ds_write_b32 v66, v37 offset:448
	ds_write_b32 v66, v38 offset:1088
	ds_write_b32 v66, v39 offset:1216
	ds_write_b32 v66, v40 offset:1344
	ds_write_b32 v66, v41 offset:1472
	ds_write_b32 v66, v42 offset:2112
	ds_write_b32 v66, v43 offset:2240
	ds_write_b32 v66, v44 offset:2368
	ds_write_b32 v66, v45 offset:2496
	ds_write_b32 v66, v46 offset:3136
	ds_write_b32 v66, v47 offset:3264
	ds_write_b32 v66, v48 offset:3392
	ds_write_b32 v66, v49 offset:3520
	s_mov_b64 exec, s[0:1]
	ds_read_b128 v[48:51], v67
	ds_read_b128 v[52:55], v67 offset:1024
	ds_read_b128 v[56:59], v67 offset:2048
	ds_read_b128 v[60:63], v67 offset:3072
	s_waitcnt lgkmcnt(3)
; __device__ __forceinline__ unsigned cvt_pk_bf16(float lo, float hi) { unsigned r; asm volatile("v_cvt_pk_bf16_f32 %0, %1, %2" : "=v"(r) : "v"(lo), "v"(hi)); return r; }
; __device__ __forceinline__ void block(const BlockRef& cur, const int j0, const int NT, const int split, const SplitRef sp, lptr lds, int tid) {
;     ...
;         if ((r32 & 1) == 0) { bf16_t* op = Ow + (size_t)orow * DM + r32;
;             *(unsigned*)(op) = cvt_pk_bf16(v0, n0); *(unsigned*)(op + 32) = cvt_pk_bf16(v1, n1); *(unsigned*)(op + 64) = cvt_pk_bf16(v2, n2); *(unsigned*)(op + 96) = cvt_pk_bf16(v3, n3); } }
	global_store_dwordx4 v162, v[48:51], s[4:5]
	s_add_u32 s4, s4, 0x8000
	s_addc_u32 s5, s5, 0
	s_waitcnt lgkmcnt(2)
	global_store_dwordx4 v162, v[52:55], s[4:5]
	s_add_u32 s4, s4, 0x8000
	s_addc_u32 s5, s5, 0
	s_waitcnt lgkmcnt(1)
	global_store_dwordx4 v162, v[56:59], s[4:5]
	s_add_u32 s4, s4, 0x8000
	s_addc_u32 s5, s5, 0
	s_waitcnt lgkmcnt(0)
	global_store_dwordx4 v162, v[60:63], s[4:5]
	s_sub_u32 s4, s4, 0x18000
	s_subb_u32 s5, s5, 0
	s_and_b64 exec, s[0:1], vcc
	ds_write_b32 v66, v18
	ds_write_b32 v66, v19 offset:128
	ds_write_b32 v66, v20 offset:256
	ds_write_b32 v66, v21 offset:384
	ds_write_b32 v66, v22 offset:1024
	ds_write_b32 v66, v23 offset:1152
	ds_write_b32 v66, v24 offset:1280
	ds_write_b32 v66, v25 offset:1408
	ds_write_b32 v66, v26 offset:2048
	ds_write_b32 v66, v27 offset:2176
	ds_write_b32 v66, v28 offset:2304
	ds_write_b32 v66, v29 offset:2432
	ds_write_b32 v66, v30 offset:3072
	ds_write_b32 v66, v31 offset:3200
	ds_write_b32 v66, v32 offset:3328
	ds_write_b32 v66, v33 offset:3456
	ds_write_b32 v66, v2 offset:64
	ds_write_b32 v66, v3 offset:192
	ds_write_b32 v66, v4 offset:320
	ds_write_b32 v66, v5 offset:448
	ds_write_b32 v66, v6 offset:1088
	ds_write_b32 v66, v7 offset:1216
	ds_write_b32 v66, v8 offset:1344
	ds_write_b32 v66, v9 offset:1472
	ds_write_b32 v66, v10 offset:2112
	ds_write_b32 v66, v11 offset:2240
	ds_write_b32 v66, v12 offset:2368
	ds_write_b32 v66, v13 offset:2496
	ds_write_b32 v66, v14 offset:3136
	ds_write_b32 v66, v15 offset:3264
	ds_write_b32 v66, v16 offset:3392
	ds_write_b32 v66, v17 offset:3520
	s_mov_b64 exec, s[0:1]
	ds_read_b128 v[4:7], v67
	ds_read_b128 v[8:11], v67 offset:1024
	ds_read_b128 v[12:15], v67 offset:2048
	ds_read_b128 v[16:19], v67 offset:3072
	s_waitcnt lgkmcnt(3)
	global_store_dwordx4 v162, v[4:7], s[4:5] offset:128
	s_add_u32 s4, s4, 0x8000
	s_addc_u32 s5, s5, 0
	s_waitcnt lgkmcnt(2)
	global_store_dwordx4 v162, v[8:11], s[4:5] offset:128
	s_add_u32 s4, s4, 0x8000
	s_addc_u32 s5, s5, 0
	s_waitcnt lgkmcnt(1)
	global_store_dwordx4 v162, v[12:15], s[4:5] offset:128
	s_add_u32 s4, s4, 0x8000
	s_addc_u32 s5, s5, 0
	s_waitcnt lgkmcnt(0)
	global_store_dwordx4 v162, v[16:19], s[4:5] offset:128
	s_branch .LBB0_821
